# K loops: s_setprio 1 issued before the pre-MMA barrier, redundant lgkmcnt(0) after it dropped, s_setprio 0 after the post-MMA barrier
# baseline (speedup 1.0000x reference)
.LBB0_79:
	s_add_u32 s30, s28, 0xfffc0080
	s_addc_u32 s31, s29, -1
	s_add_i32 s63, 0, 0x10000
	s_cmp_eq_u32 s62, 12
	s_cselect_b32 s35, s5, s31
	s_cselect_b32 s34, s21, s30
	v_add_u32_e32 v146, s63, v148
	s_cselect_b32 s31, s19, s61
	s_cselect_b32 s30, s27, s60
	s_add_i32 s66, 0, 0x14000
	ds_read_b128 v[142:145], v146
	ds_read_b128 v[152:155], v146 offset:1024
	ds_read_b128 v[156:159], v146 offset:2048
	ds_read_b128 v[160:163], v146 offset:3072
	v_add_u32_e32 v146, s66, v148
	ds_read_b128 v[164:167], v146
	ds_read_b128 v[168:171], v146 offset:1024
	ds_read_b128 v[172:175], v146 offset:2048
	ds_read_b128 v[176:179], v146 offset:3072
	v_lshl_add_u64 v[146:147], s[28:29], 0, v[138:139]
	s_add_i32 m0, s38, 0xc000
	ds_read_b128 v[180:183], v150
	ds_read_b128 v[184:187], v150 offset:1024
	ds_read_b128 v[188:191], v150 offset:2048
	ds_read_b128 v[192:195], v150 offset:3072
	ds_read_b128 v[196:199], v150 offset:4096
	ds_read_b128 v[200:203], v150 offset:5120
	ds_read_b128 v[204:207], v150 offset:6144
	ds_read_b128 v[208:211], v150 offset:7168
	global_load_lds_dwordx4 v[146:147], off
	v_lshl_add_u64 v[146:147], s[28:29], 0, v[140:141]
	s_add_i32 m0, s38, 0xe000
	s_nop 0
	global_load_lds_dwordx4 v[146:147], off
	s_waitcnt vmcnt(8)
	s_waitcnt lgkmcnt(0)
	s_setprio 1
	s_barrier
	v_mfma_f32_16x16x32_bf16 v[130:133], v[142:145], v[180:183], v[130:133]
	v_mfma_f32_16x16x32_bf16 v[126:129], v[156:159], v[180:183], v[126:129]
	v_mfma_f32_16x16x32_bf16 v[114:117], v[142:145], v[188:191], v[114:117]
	v_mfma_f32_16x16x32_bf16 v[110:113], v[156:159], v[188:191], v[110:113]
	v_mfma_f32_16x16x32_bf16 v[98:101], v[142:145], v[196:199], v[98:101]
	v_mfma_f32_16x16x32_bf16 v[94:97], v[156:159], v[196:199], v[94:97]
	v_mfma_f32_16x16x32_bf16 v[82:85], v[142:145], v[204:207], v[82:85]
	v_mfma_f32_16x16x32_bf16 v[78:81], v[156:159], v[204:207], v[78:81]
	v_mfma_f32_16x16x32_bf16 v[130:133], v[152:155], v[184:187], v[130:133]
	v_mfma_f32_16x16x32_bf16 v[126:129], v[160:163], v[184:187], v[126:129]
	v_mfma_f32_16x16x32_bf16 v[114:117], v[152:155], v[192:195], v[114:117]
	v_mfma_f32_16x16x32_bf16 v[110:113], v[160:163], v[192:195], v[110:113]
	v_mfma_f32_16x16x32_bf16 v[98:101], v[152:155], v[200:203], v[98:101]
	v_mfma_f32_16x16x32_bf16 v[94:97], v[160:163], v[200:203], v[94:97]
	v_mfma_f32_16x16x32_bf16 v[82:85], v[152:155], v[208:211], v[82:85]
	v_mfma_f32_16x16x32_bf16 v[78:81], v[160:163], v[208:211], v[78:81]
	s_setprio 0
	s_setprio 1
	v_mfma_f32_16x16x32_bf16 v[122:125], v[164:167], v[180:183], v[122:125]
	v_mfma_f32_16x16x32_bf16 v[118:121], v[172:175], v[180:183], v[118:121]
	v_mfma_f32_16x16x32_bf16 v[106:109], v[164:167], v[188:191], v[106:109]
	v_mfma_f32_16x16x32_bf16 v[102:105], v[172:175], v[188:191], v[102:105]
	v_mfma_f32_16x16x32_bf16 v[90:93], v[164:167], v[196:199], v[90:93]
	v_mfma_f32_16x16x32_bf16 v[86:89], v[172:175], v[196:199], v[86:89]
	v_mfma_f32_16x16x32_bf16 v[74:77], v[164:167], v[204:207], v[74:77]
	v_mfma_f32_16x16x32_bf16 v[70:73], v[172:175], v[204:207], v[70:73]
	v_mfma_f32_16x16x32_bf16 v[122:125], v[168:171], v[184:187], v[122:125]
	v_mfma_f32_16x16x32_bf16 v[118:121], v[176:179], v[184:187], v[118:121]
	v_mfma_f32_16x16x32_bf16 v[106:109], v[168:171], v[192:195], v[106:109]
	v_mfma_f32_16x16x32_bf16 v[102:105], v[176:179], v[192:195], v[102:105]
	v_mfma_f32_16x16x32_bf16 v[90:93], v[168:171], v[200:203], v[90:93]
	v_mfma_f32_16x16x32_bf16 v[86:89], v[176:179], v[200:203], v[86:89]
	v_mfma_f32_16x16x32_bf16 v[74:77], v[168:171], v[208:211], v[74:77]
	v_mfma_f32_16x16x32_bf16 v[70:73], v[176:179], v[208:211], v[70:73]
	s_barrier
	s_setprio 0
	s_add_i32 s63, s63, s37
	v_lshl_add_u64 v[146:147], s[30:31], 0, v[0:1]
	s_mov_b32 m0, s63
	ds_read_b128 v[180:183], v150 offset:16384
	ds_read_b128 v[184:187], v150 offset:17408
	ds_read_b128 v[188:191], v150 offset:18432
	ds_read_b128 v[192:195], v150 offset:19456
	ds_read_b128 v[196:199], v150 offset:20480
	ds_read_b128 v[200:203], v150 offset:21504
	ds_read_b128 v[204:207], v150 offset:22528
	ds_read_b128 v[208:211], v150 offset:23552
	global_load_lds_dwordx4 v[146:147], off
	s_add_i32 m0, s63, 0x2000
	s_add_u32 s64, s30, 0x580000
	v_lshl_add_u64 v[212:213], s[30:31], 0, v[136:137]
	s_addc_u32 s65, s31, 0
	s_add_i32 s63, s66, s37
	global_load_lds_dwordx4 v[212:213], off
	v_lshl_add_u64 v[214:215], s[64:65], 0, v[0:1]
	s_mov_b32 m0, s63
	v_lshl_add_u64 v[216:217], s[34:35], 0, v[134:135]
	global_load_lds_dwordx4 v[214:215], off
	v_lshl_add_u64 v[214:215], s[64:65], 0, v[136:137]
	s_add_i32 m0, s63, 0x2000
	s_nop 0
	global_load_lds_dwordx4 v[214:215], off
	v_lshl_add_u64 v[214:215], s[34:35], 0, v[2:3]
	s_mov_b32 m0, s38
	s_nop 0
	global_load_lds_dwordx4 v[214:215], off
	s_mov_b32 m0, s39
	s_nop 0
	global_load_lds_dwordx4 v[216:217], off
	s_waitcnt vmcnt(8)
	s_waitcnt lgkmcnt(0)
	s_setprio 1
	s_barrier
	v_mfma_f32_16x16x32_bf16 v[66:69], v[142:145], v[180:183], v[66:69]
	v_mfma_f32_16x16x32_bf16 v[62:65], v[156:159], v[180:183], v[62:65]
	v_mfma_f32_16x16x32_bf16 v[50:53], v[142:145], v[188:191], v[50:53]
	v_mfma_f32_16x16x32_bf16 v[46:49], v[156:159], v[188:191], v[46:49]
	v_mfma_f32_16x16x32_bf16 v[34:37], v[142:145], v[196:199], v[34:37]
	v_mfma_f32_16x16x32_bf16 v[30:33], v[156:159], v[196:199], v[30:33]
	v_mfma_f32_16x16x32_bf16 v[18:21], v[142:145], v[204:207], v[18:21]
	v_mfma_f32_16x16x32_bf16 v[14:17], v[156:159], v[204:207], v[14:17]
	v_mfma_f32_16x16x32_bf16 v[66:69], v[152:155], v[184:187], v[66:69]
	v_mfma_f32_16x16x32_bf16 v[62:65], v[160:163], v[184:187], v[62:65]
	v_mfma_f32_16x16x32_bf16 v[50:53], v[152:155], v[192:195], v[50:53]
	v_mfma_f32_16x16x32_bf16 v[46:49], v[160:163], v[192:195], v[46:49]
	v_mfma_f32_16x16x32_bf16 v[34:37], v[152:155], v[200:203], v[34:37]
	v_mfma_f32_16x16x32_bf16 v[30:33], v[160:163], v[200:203], v[30:33]
	v_mfma_f32_16x16x32_bf16 v[18:21], v[152:155], v[208:211], v[18:21]
	v_mfma_f32_16x16x32_bf16 v[14:17], v[160:163], v[208:211], v[14:17]
	s_setprio 0
	s_setprio 1
	v_mfma_f32_16x16x32_bf16 v[58:61], v[164:167], v[180:183], v[58:61]
	v_mfma_f32_16x16x32_bf16 v[54:57], v[172:175], v[180:183], v[54:57]
	v_mfma_f32_16x16x32_bf16 v[42:45], v[164:167], v[188:191], v[42:45]
	v_mfma_f32_16x16x32_bf16 v[38:41], v[172:175], v[188:191], v[38:41]
	v_mfma_f32_16x16x32_bf16 v[26:29], v[164:167], v[196:199], v[26:29]
	v_mfma_f32_16x16x32_bf16 v[22:25], v[172:175], v[196:199], v[22:25]
	v_mfma_f32_16x16x32_bf16 v[10:13], v[164:167], v[204:207], v[10:13]
	v_mfma_f32_16x16x32_bf16 v[6:9], v[172:175], v[204:207], v[6:9]
	v_mfma_f32_16x16x32_bf16 v[58:61], v[168:171], v[184:187], v[58:61]
	v_mfma_f32_16x16x32_bf16 v[54:57], v[176:179], v[184:187], v[54:57]
	v_mfma_f32_16x16x32_bf16 v[42:45], v[168:171], v[192:195], v[42:45]
	v_mfma_f32_16x16x32_bf16 v[38:41], v[176:179], v[192:195], v[38:41]
	v_mfma_f32_16x16x32_bf16 v[26:29], v[168:171], v[200:203], v[26:29]
	v_mfma_f32_16x16x32_bf16 v[22:25], v[176:179], v[200:203], v[22:25]
	v_mfma_f32_16x16x32_bf16 v[10:13], v[168:171], v[208:211], v[10:13]
	v_mfma_f32_16x16x32_bf16 v[6:9], v[176:179], v[208:211], v[6:9]
	s_barrier
	s_setprio 0
	s_add_i32 s63, 0, 0x18000
	v_add_u32_e32 v151, s63, v148
	s_add_i32 s64, 0, 0x1c000
	ds_read_b128 v[142:145], v151
	ds_read_b128 v[152:155], v151 offset:1024
	ds_read_b128 v[156:159], v151 offset:2048
	ds_read_b128 v[160:163], v151 offset:3072
	v_add_u32_e32 v151, s64, v148
	ds_read_b128 v[164:167], v151
	ds_read_b128 v[168:171], v151 offset:1024
	ds_read_b128 v[172:175], v151 offset:2048
	ds_read_b128 v[176:179], v151 offset:3072
	s_add_u32 s34, s34, 0x40000
	s_addc_u32 s35, s35, 0
	s_mov_b32 m0, s41
	v_lshl_add_u64 v[220:221], s[34:35], 0, v[2:3]
	ds_read_b128 v[180:183], v150 offset:32768
	ds_read_b128 v[184:187], v150 offset:33792
	ds_read_b128 v[188:191], v150 offset:34816
	ds_read_b128 v[192:195], v150 offset:35840
	ds_read_b128 v[196:199], v150 offset:36864
	ds_read_b128 v[200:203], v150 offset:37888
	ds_read_b128 v[204:207], v150 offset:38912
	ds_read_b128 v[208:211], v150 offset:39936
	global_load_lds_dwordx4 v[220:221], off
	v_lshl_add_u64 v[220:221], s[34:35], 0, v[134:135]
	s_mov_b32 m0, s42
	s_nop 0
	global_load_lds_dwordx4 v[220:221], off
	s_waitcnt vmcnt(8)
	s_waitcnt lgkmcnt(0)
	s_setprio 1
	s_barrier
	v_mfma_f32_16x16x32_bf16 v[130:133], v[142:145], v[180:183], v[130:133]
	v_mfma_f32_16x16x32_bf16 v[126:129], v[156:159], v[180:183], v[126:129]
	v_mfma_f32_16x16x32_bf16 v[114:117], v[142:145], v[188:191], v[114:117]
	v_mfma_f32_16x16x32_bf16 v[110:113], v[156:159], v[188:191], v[110:113]
	v_mfma_f32_16x16x32_bf16 v[98:101], v[142:145], v[196:199], v[98:101]
	v_mfma_f32_16x16x32_bf16 v[94:97], v[156:159], v[196:199], v[94:97]
	v_mfma_f32_16x16x32_bf16 v[82:85], v[142:145], v[204:207], v[82:85]
	v_mfma_f32_16x16x32_bf16 v[78:81], v[156:159], v[204:207], v[78:81]
	v_mfma_f32_16x16x32_bf16 v[130:133], v[152:155], v[184:187], v[130:133]
	v_mfma_f32_16x16x32_bf16 v[126:129], v[160:163], v[184:187], v[126:129]
	v_mfma_f32_16x16x32_bf16 v[114:117], v[152:155], v[192:195], v[114:117]
	v_mfma_f32_16x16x32_bf16 v[110:113], v[160:163], v[192:195], v[110:113]
	v_mfma_f32_16x16x32_bf16 v[98:101], v[152:155], v[200:203], v[98:101]
	v_mfma_f32_16x16x32_bf16 v[94:97], v[160:163], v[200:203], v[94:97]
	v_mfma_f32_16x16x32_bf16 v[82:85], v[152:155], v[208:211], v[82:85]
	v_mfma_f32_16x16x32_bf16 v[78:81], v[160:163], v[208:211], v[78:81]
	s_setprio 0
	s_setprio 1
	v_mfma_f32_16x16x32_bf16 v[122:125], v[164:167], v[180:183], v[122:125]
	v_mfma_f32_16x16x32_bf16 v[118:121], v[172:175], v[180:183], v[118:121]
	v_mfma_f32_16x16x32_bf16 v[106:109], v[164:167], v[188:191], v[106:109]
	v_mfma_f32_16x16x32_bf16 v[102:105], v[172:175], v[188:191], v[102:105]
	v_mfma_f32_16x16x32_bf16 v[90:93], v[164:167], v[196:199], v[90:93]
	v_mfma_f32_16x16x32_bf16 v[86:89], v[172:175], v[196:199], v[86:89]
	v_mfma_f32_16x16x32_bf16 v[74:77], v[164:167], v[204:207], v[74:77]
	v_mfma_f32_16x16x32_bf16 v[70:73], v[172:175], v[204:207], v[70:73]
	v_mfma_f32_16x16x32_bf16 v[122:125], v[168:171], v[184:187], v[122:125]
	v_mfma_f32_16x16x32_bf16 v[118:121], v[176:179], v[184:187], v[118:121]
	v_mfma_f32_16x16x32_bf16 v[106:109], v[168:171], v[192:195], v[106:109]
	v_mfma_f32_16x16x32_bf16 v[102:105], v[176:179], v[192:195], v[102:105]
	v_mfma_f32_16x16x32_bf16 v[90:93], v[168:171], v[200:203], v[90:93]
	v_mfma_f32_16x16x32_bf16 v[86:89], v[176:179], v[200:203], v[86:89]
	v_mfma_f32_16x16x32_bf16 v[74:77], v[168:171], v[208:211], v[74:77]
	v_mfma_f32_16x16x32_bf16 v[70:73], v[176:179], v[208:211], v[70:73]
	s_barrier
	s_setprio 0
	s_add_i32 s34, s63, s37
	v_lshl_add_u64 v[146:147], v[146:147], 0, s[50:51]
	s_mov_b32 m0, s34
	ds_read_b128 v[180:183], v150 offset:49152
	ds_read_b128 v[184:187], v150 offset:50176
	ds_read_b128 v[188:191], v150 offset:51200
	ds_read_b128 v[192:195], v150 offset:52224
	ds_read_b128 v[196:199], v150 offset:53248
	ds_read_b128 v[200:203], v150 offset:54272
	ds_read_b128 v[204:207], v150 offset:55296
	ds_read_b128 v[208:211], v150 offset:56320
	global_load_lds_dwordx4 v[146:147], off
	s_add_i32 m0, s34, 0x2000
	s_add_u32 s30, s30, 0x580080
	v_lshl_add_u64 v[146:147], v[212:213], 0, s[50:51]
	s_addc_u32 s31, s31, 0
	s_add_i32 s34, s64, s37
	global_load_lds_dwordx4 v[146:147], off
	v_lshl_add_u64 v[146:147], s[30:31], 0, v[0:1]
	s_mov_b32 m0, s34
	s_nop 0
	global_load_lds_dwordx4 v[146:147], off
	v_lshl_add_u64 v[146:147], s[30:31], 0, v[136:137]
	s_add_i32 m0, s34, 0x2000
	s_nop 0
	global_load_lds_dwordx4 v[146:147], off
	v_lshl_add_u64 v[146:147], v[214:215], 0, s[50:51]
	s_mov_b32 m0, s44
	s_nop 0
	global_load_lds_dwordx4 v[146:147], off
	v_lshl_add_u64 v[146:147], v[216:217], 0, s[50:51]
	s_mov_b32 m0, s45
	s_nop 0
	global_load_lds_dwordx4 v[146:147], off
	s_waitcnt vmcnt(8)
	s_waitcnt lgkmcnt(0)
	s_setprio 1
	s_barrier
	v_mfma_f32_16x16x32_bf16 v[66:69], v[142:145], v[180:183], v[66:69]
	v_mfma_f32_16x16x32_bf16 v[62:65], v[156:159], v[180:183], v[62:65]
	v_mfma_f32_16x16x32_bf16 v[50:53], v[142:145], v[188:191], v[50:53]
	v_mfma_f32_16x16x32_bf16 v[46:49], v[156:159], v[188:191], v[46:49]
	v_mfma_f32_16x16x32_bf16 v[34:37], v[142:145], v[196:199], v[34:37]
	v_mfma_f32_16x16x32_bf16 v[30:33], v[156:159], v[196:199], v[30:33]
	v_mfma_f32_16x16x32_bf16 v[18:21], v[142:145], v[204:207], v[18:21]
	v_mfma_f32_16x16x32_bf16 v[14:17], v[156:159], v[204:207], v[14:17]
	v_mfma_f32_16x16x32_bf16 v[66:69], v[152:155], v[184:187], v[66:69]
	v_mfma_f32_16x16x32_bf16 v[62:65], v[160:163], v[184:187], v[62:65]
	v_mfma_f32_16x16x32_bf16 v[50:53], v[152:155], v[192:195], v[50:53]
	v_mfma_f32_16x16x32_bf16 v[46:49], v[160:163], v[192:195], v[46:49]
	v_mfma_f32_16x16x32_bf16 v[34:37], v[152:155], v[200:203], v[34:37]
	v_mfma_f32_16x16x32_bf16 v[30:33], v[160:163], v[200:203], v[30:33]
	v_mfma_f32_16x16x32_bf16 v[18:21], v[152:155], v[208:211], v[18:21]
	v_mfma_f32_16x16x32_bf16 v[14:17], v[160:163], v[208:211], v[14:17]
	s_setprio 0
	s_setprio 1
	v_mfma_f32_16x16x32_bf16 v[58:61], v[164:167], v[180:183], v[58:61]
	v_mfma_f32_16x16x32_bf16 v[54:57], v[172:175], v[180:183], v[54:57]
	v_mfma_f32_16x16x32_bf16 v[42:45], v[164:167], v[188:191], v[42:45]
	v_mfma_f32_16x16x32_bf16 v[38:41], v[172:175], v[188:191], v[38:41]
	v_mfma_f32_16x16x32_bf16 v[26:29], v[164:167], v[196:199], v[26:29]
	v_mfma_f32_16x16x32_bf16 v[22:25], v[172:175], v[196:199], v[22:25]
	v_mfma_f32_16x16x32_bf16 v[10:13], v[164:167], v[204:207], v[10:13]
	v_mfma_f32_16x16x32_bf16 v[6:9], v[172:175], v[204:207], v[6:9]
	v_mfma_f32_16x16x32_bf16 v[58:61], v[168:171], v[184:187], v[58:61]
	v_mfma_f32_16x16x32_bf16 v[54:57], v[176:179], v[184:187], v[54:57]
	v_mfma_f32_16x16x32_bf16 v[42:45], v[168:171], v[192:195], v[42:45]
	v_mfma_f32_16x16x32_bf16 v[38:41], v[176:179], v[192:195], v[38:41]
	v_mfma_f32_16x16x32_bf16 v[26:29], v[168:171], v[200:203], v[26:29]
	v_mfma_f32_16x16x32_bf16 v[22:25], v[176:179], v[200:203], v[22:25]
	v_mfma_f32_16x16x32_bf16 v[10:13], v[168:171], v[208:211], v[10:13]
	v_mfma_f32_16x16x32_bf16 v[6:9], v[176:179], v[208:211], v[6:9]
	s_barrier
	s_setprio 0
	s_add_i32 s62, s62, 2
	s_add_u32 s28, s28, 0x100
	s_addc_u32 s29, s29, 0
	s_add_u32 s60, s60, 0x100
	s_addc_u32 s61, s61, 0
	s_cmp_gt_u32 s62, 13
	s_cbranch_scc0 .LBB0_79
	s_and_b64 vcc, exec, s[16:17]
	s_cbranch_vccz .LBB0_82
	s_barrier

.LBB0_205:
	s_add_u32 s28, s26, 0xfffc0080
	s_addc_u32 s29, s27, -1
	s_add_i32 s60, 0, 0x10000
	s_cmp_eq_u32 s59, 12
	s_cselect_b32 s31, s7, s29
	s_cselect_b32 s30, s19, s28
	v_add_u32_e32 v0, s60, v164
	s_cselect_b32 s29, s17, s58
	s_cselect_b32 s28, s25, s48
	s_add_i32 s62, 0, 0x14000
	ds_read_b128 v[46:49], v0
	ds_read_b128 v[50:53], v0 offset:1024
	ds_read_b128 v[54:57], v0 offset:2048
	ds_read_b128 v[58:61], v0 offset:3072
	v_add_u32_e32 v0, s62, v164
	ds_read_b128 v[160:163], v0
	ds_read_b128 v[168:171], v0 offset:1024
	ds_read_b128 v[172:175], v0 offset:2048
	ds_read_b128 v[176:179], v0 offset:3072
	v_lshl_add_u64 v[212:213], s[26:27], 0, v[156:157]
	s_add_i32 m0, s36, 0xc000
	ds_read_b128 v[180:183], v166
	ds_read_b128 v[184:187], v166 offset:1024
	ds_read_b128 v[188:191], v166 offset:2048
	ds_read_b128 v[192:195], v166 offset:3072
	ds_read_b128 v[196:199], v166 offset:4096
	ds_read_b128 v[200:203], v166 offset:5120
	ds_read_b128 v[204:207], v166 offset:6144
	ds_read_b128 v[208:211], v166 offset:7168
	global_load_lds_dwordx4 v[212:213], off
	v_lshl_add_u64 v[212:213], s[26:27], 0, v[158:159]
	s_add_i32 m0, s36, 0xe000
	s_nop 0
	global_load_lds_dwordx4 v[212:213], off
	s_waitcnt vmcnt(8)
	s_waitcnt lgkmcnt(0)
	s_setprio 1
	s_barrier
	v_mfma_f32_16x16x32_bf16 v[146:149], v[46:49], v[180:183], v[146:149]
	v_mfma_f32_16x16x32_bf16 v[142:145], v[54:57], v[180:183], v[142:145]
	v_mfma_f32_16x16x32_bf16 v[130:133], v[46:49], v[188:191], v[130:133]
	v_mfma_f32_16x16x32_bf16 v[126:129], v[54:57], v[188:191], v[126:129]
	v_mfma_f32_16x16x32_bf16 v[114:117], v[46:49], v[196:199], v[114:117]
	v_mfma_f32_16x16x32_bf16 v[110:113], v[54:57], v[196:199], v[110:113]
	v_mfma_f32_16x16x32_bf16 v[98:101], v[46:49], v[204:207], v[98:101]
	v_mfma_f32_16x16x32_bf16 v[94:97], v[54:57], v[204:207], v[94:97]
	v_mfma_f32_16x16x32_bf16 v[146:149], v[50:53], v[184:187], v[146:149]
	v_mfma_f32_16x16x32_bf16 v[142:145], v[58:61], v[184:187], v[142:145]
	v_mfma_f32_16x16x32_bf16 v[130:133], v[50:53], v[192:195], v[130:133]
	v_mfma_f32_16x16x32_bf16 v[126:129], v[58:61], v[192:195], v[126:129]
	v_mfma_f32_16x16x32_bf16 v[114:117], v[50:53], v[200:203], v[114:117]
	v_mfma_f32_16x16x32_bf16 v[110:113], v[58:61], v[200:203], v[110:113]
	v_mfma_f32_16x16x32_bf16 v[98:101], v[50:53], v[208:211], v[98:101]
	v_mfma_f32_16x16x32_bf16 v[94:97], v[58:61], v[208:211], v[94:97]
	s_setprio 0
	s_setprio 1
	v_mfma_f32_16x16x32_bf16 v[138:141], v[160:163], v[180:183], v[138:141]
	v_mfma_f32_16x16x32_bf16 v[134:137], v[172:175], v[180:183], v[134:137]
	v_mfma_f32_16x16x32_bf16 v[122:125], v[160:163], v[188:191], v[122:125]
	v_mfma_f32_16x16x32_bf16 v[118:121], v[172:175], v[188:191], v[118:121]
	v_mfma_f32_16x16x32_bf16 v[106:109], v[160:163], v[196:199], v[106:109]
	v_mfma_f32_16x16x32_bf16 v[102:105], v[172:175], v[196:199], v[102:105]
	v_mfma_f32_16x16x32_bf16 v[90:93], v[160:163], v[204:207], v[90:93]
	v_mfma_f32_16x16x32_bf16 v[86:89], v[172:175], v[204:207], v[86:89]
	v_mfma_f32_16x16x32_bf16 v[138:141], v[168:171], v[184:187], v[138:141]
	v_mfma_f32_16x16x32_bf16 v[134:137], v[176:179], v[184:187], v[134:137]
	v_mfma_f32_16x16x32_bf16 v[122:125], v[168:171], v[192:195], v[122:125]
	v_mfma_f32_16x16x32_bf16 v[118:121], v[176:179], v[192:195], v[118:121]
	v_mfma_f32_16x16x32_bf16 v[106:109], v[168:171], v[200:203], v[106:109]
	v_mfma_f32_16x16x32_bf16 v[102:105], v[176:179], v[200:203], v[102:105]
	v_mfma_f32_16x16x32_bf16 v[90:93], v[168:171], v[208:211], v[90:93]
	v_mfma_f32_16x16x32_bf16 v[86:89], v[176:179], v[208:211], v[86:89]
	s_barrier
	s_setprio 0
	s_add_i32 s60, s60, s35
	v_lshl_add_u64 v[212:213], s[28:29], 0, v[150:151]
	s_mov_b32 m0, s60
	ds_read_b128 v[180:183], v166 offset:16384
	ds_read_b128 v[184:187], v166 offset:17408
	ds_read_b128 v[188:191], v166 offset:18432
	ds_read_b128 v[192:195], v166 offset:19456
	ds_read_b128 v[196:199], v166 offset:20480
	ds_read_b128 v[200:203], v166 offset:21504
	ds_read_b128 v[204:207], v166 offset:22528
	ds_read_b128 v[208:211], v166 offset:23552
	global_load_lds_dwordx4 v[212:213], off
	s_add_i32 m0, s60, 0x2000
	s_add_u32 s60, s28, 0x40000
	v_lshl_add_u64 v[214:215], s[28:29], 0, v[154:155]
	s_addc_u32 s61, s29, 0
	s_add_i32 s62, s62, s35
	global_load_lds_dwordx4 v[214:215], off
	v_lshl_add_u64 v[216:217], s[60:61], 0, v[150:151]
	s_mov_b32 m0, s62
	v_lshl_add_u64 v[220:221], s[30:31], 0, v[152:153]
	global_load_lds_dwordx4 v[216:217], off
	v_lshl_add_u64 v[216:217], s[60:61], 0, v[154:155]
	s_add_i32 m0, s62, 0x2000
	s_nop 0
	global_load_lds_dwordx4 v[216:217], off
	v_lshl_add_u64 v[216:217], s[30:31], 0, v[2:3]
	s_mov_b32 m0, s36
	s_nop 0
	global_load_lds_dwordx4 v[216:217], off
	s_mov_b32 m0, s37
	s_nop 0
	global_load_lds_dwordx4 v[220:221], off
	s_waitcnt vmcnt(8)
	s_waitcnt lgkmcnt(0)
	s_setprio 1
	s_barrier
	v_mfma_f32_16x16x32_bf16 v[82:85], v[46:49], v[180:183], v[82:85]
	v_mfma_f32_16x16x32_bf16 v[78:81], v[54:57], v[180:183], v[78:81]
	v_mfma_f32_16x16x32_bf16 v[66:69], v[46:49], v[188:191], v[66:69]
	v_mfma_f32_16x16x32_bf16 v[62:65], v[54:57], v[188:191], v[62:65]
	v_mfma_f32_16x16x32_bf16 v[34:37], v[46:49], v[196:199], v[34:37]
	v_mfma_f32_16x16x32_bf16 v[30:33], v[54:57], v[196:199], v[30:33]
	v_mfma_f32_16x16x32_bf16 v[18:21], v[46:49], v[204:207], v[18:21]
	v_mfma_f32_16x16x32_bf16 v[14:17], v[54:57], v[204:207], v[14:17]
	v_mfma_f32_16x16x32_bf16 v[82:85], v[50:53], v[184:187], v[82:85]
	v_mfma_f32_16x16x32_bf16 v[78:81], v[58:61], v[184:187], v[78:81]
	v_mfma_f32_16x16x32_bf16 v[66:69], v[50:53], v[192:195], v[66:69]
	v_mfma_f32_16x16x32_bf16 v[62:65], v[58:61], v[192:195], v[62:65]
	v_mfma_f32_16x16x32_bf16 v[34:37], v[50:53], v[200:203], v[34:37]
	v_mfma_f32_16x16x32_bf16 v[30:33], v[58:61], v[200:203], v[30:33]
	v_mfma_f32_16x16x32_bf16 v[18:21], v[50:53], v[208:211], v[18:21]
	v_mfma_f32_16x16x32_bf16 v[14:17], v[58:61], v[208:211], v[14:17]
	s_setprio 0
	s_setprio 1
	v_mfma_f32_16x16x32_bf16 v[42:45], v[160:163], v[188:191], v[42:45]
	v_mfma_f32_16x16x32_bf16 v[38:41], v[172:175], v[188:191], v[38:41]
	v_mfma_f32_16x16x32_bf16 v[26:29], v[160:163], v[196:199], v[26:29]
	v_mfma_f32_16x16x32_bf16 v[22:25], v[172:175], v[196:199], v[22:25]
	v_mfma_f32_16x16x32_bf16 v[10:13], v[160:163], v[204:207], v[10:13]
	v_mfma_f32_16x16x32_bf16 v[6:9], v[172:175], v[204:207], v[6:9]
	v_mfma_f32_16x16x32_bf16 v[46:49], v[160:163], v[180:183], v[74:77]
	v_mfma_f32_16x16x32_bf16 v[50:53], v[172:175], v[180:183], v[70:73]
	v_mfma_f32_16x16x32_bf16 v[42:45], v[168:171], v[192:195], v[42:45]
	v_mfma_f32_16x16x32_bf16 v[38:41], v[176:179], v[192:195], v[38:41]
	v_mfma_f32_16x16x32_bf16 v[26:29], v[168:171], v[200:203], v[26:29]
	v_mfma_f32_16x16x32_bf16 v[22:25], v[176:179], v[200:203], v[22:25]
	v_mfma_f32_16x16x32_bf16 v[10:13], v[168:171], v[208:211], v[10:13]
	v_mfma_f32_16x16x32_bf16 v[6:9], v[176:179], v[208:211], v[6:9]
	v_mfma_f32_16x16x32_bf16 v[46:49], v[168:171], v[184:187], v[46:49]
	v_mfma_f32_16x16x32_bf16 v[50:53], v[176:179], v[184:187], v[50:53]
	s_barrier
	s_setprio 0
	s_add_i32 s60, 0, 0x18000
	v_add_u32_e32 v0, s60, v164
	s_add_i32 s61, 0, 0x1c000
	ds_read_b128 v[54:57], v0
	ds_read_b128 v[58:61], v0 offset:1024
	ds_read_b128 v[70:73], v0 offset:2048
	ds_read_b128 v[74:77], v0 offset:3072
	v_add_u32_e32 v0, s61, v164
	ds_read_b128 v[160:163], v0
	ds_read_b128 v[168:171], v0 offset:1024
	ds_read_b128 v[172:175], v0 offset:2048
	ds_read_b128 v[176:179], v0 offset:3072
	s_add_u32 s30, s30, 0x40000
	s_addc_u32 s31, s31, 0
	s_mov_b32 m0, s38
	v_lshl_add_u64 v[222:223], s[30:31], 0, v[2:3]
	ds_read_b128 v[180:183], v166 offset:32768
	ds_read_b128 v[184:187], v166 offset:33792
	ds_read_b128 v[188:191], v166 offset:34816
	ds_read_b128 v[192:195], v166 offset:35840
	ds_read_b128 v[196:199], v166 offset:36864
	ds_read_b128 v[200:203], v166 offset:37888
	ds_read_b128 v[204:207], v166 offset:38912
	ds_read_b128 v[208:211], v166 offset:39936
	global_load_lds_dwordx4 v[222:223], off
	v_lshl_add_u64 v[222:223], s[30:31], 0, v[152:153]
	s_mov_b32 m0, s39
	s_nop 0
	global_load_lds_dwordx4 v[222:223], off
	s_waitcnt vmcnt(8)
	s_waitcnt lgkmcnt(0)
	s_setprio 1
	s_barrier
	v_mfma_f32_16x16x32_bf16 v[146:149], v[54:57], v[180:183], v[146:149]
	v_mfma_f32_16x16x32_bf16 v[142:145], v[70:73], v[180:183], v[142:145]
	v_mfma_f32_16x16x32_bf16 v[130:133], v[54:57], v[188:191], v[130:133]
	v_mfma_f32_16x16x32_bf16 v[126:129], v[70:73], v[188:191], v[126:129]
	v_mfma_f32_16x16x32_bf16 v[114:117], v[54:57], v[196:199], v[114:117]
	v_mfma_f32_16x16x32_bf16 v[110:113], v[70:73], v[196:199], v[110:113]
	v_mfma_f32_16x16x32_bf16 v[98:101], v[54:57], v[204:207], v[98:101]
	v_mfma_f32_16x16x32_bf16 v[94:97], v[70:73], v[204:207], v[94:97]
	v_mfma_f32_16x16x32_bf16 v[146:149], v[58:61], v[184:187], v[146:149]
	v_mfma_f32_16x16x32_bf16 v[142:145], v[74:77], v[184:187], v[142:145]
	v_mfma_f32_16x16x32_bf16 v[130:133], v[58:61], v[192:195], v[130:133]
	v_mfma_f32_16x16x32_bf16 v[126:129], v[74:77], v[192:195], v[126:129]
	v_mfma_f32_16x16x32_bf16 v[114:117], v[58:61], v[200:203], v[114:117]
	v_mfma_f32_16x16x32_bf16 v[110:113], v[74:77], v[200:203], v[110:113]
	v_mfma_f32_16x16x32_bf16 v[98:101], v[58:61], v[208:211], v[98:101]
	v_mfma_f32_16x16x32_bf16 v[94:97], v[74:77], v[208:211], v[94:97]
	s_setprio 0
	s_setprio 1
	v_mfma_f32_16x16x32_bf16 v[138:141], v[160:163], v[180:183], v[138:141]
	v_mfma_f32_16x16x32_bf16 v[134:137], v[172:175], v[180:183], v[134:137]
	v_mfma_f32_16x16x32_bf16 v[122:125], v[160:163], v[188:191], v[122:125]
	v_mfma_f32_16x16x32_bf16 v[118:121], v[172:175], v[188:191], v[118:121]
	v_mfma_f32_16x16x32_bf16 v[106:109], v[160:163], v[196:199], v[106:109]
	v_mfma_f32_16x16x32_bf16 v[102:105], v[172:175], v[196:199], v[102:105]
	v_mfma_f32_16x16x32_bf16 v[90:93], v[160:163], v[204:207], v[90:93]
	v_mfma_f32_16x16x32_bf16 v[86:89], v[172:175], v[204:207], v[86:89]
	v_mfma_f32_16x16x32_bf16 v[138:141], v[168:171], v[184:187], v[138:141]
	v_mfma_f32_16x16x32_bf16 v[134:137], v[176:179], v[184:187], v[134:137]
	v_mfma_f32_16x16x32_bf16 v[122:125], v[168:171], v[192:195], v[122:125]
	v_mfma_f32_16x16x32_bf16 v[118:121], v[176:179], v[192:195], v[118:121]
	v_mfma_f32_16x16x32_bf16 v[106:109], v[168:171], v[200:203], v[106:109]
	v_mfma_f32_16x16x32_bf16 v[102:105], v[176:179], v[200:203], v[102:105]
	v_mfma_f32_16x16x32_bf16 v[90:93], v[168:171], v[208:211], v[90:93]
	v_mfma_f32_16x16x32_bf16 v[86:89], v[176:179], v[208:211], v[86:89]
	s_barrier
	s_setprio 0
	s_add_i32 s30, s60, s35
	v_lshl_add_u64 v[212:213], v[212:213], 0, s[50:51]
	s_mov_b32 m0, s30
	ds_read_b128 v[180:183], v166 offset:49152
	ds_read_b128 v[184:187], v166 offset:50176
	ds_read_b128 v[188:191], v166 offset:51200
	ds_read_b128 v[192:195], v166 offset:52224
	ds_read_b128 v[196:199], v166 offset:53248
	ds_read_b128 v[200:203], v166 offset:54272
	ds_read_b128 v[204:207], v166 offset:55296
	ds_read_b128 v[208:211], v166 offset:56320
	global_load_lds_dwordx4 v[212:213], off
	s_add_i32 m0, s30, 0x2000
	s_add_u32 s28, s28, 0x40080
	v_lshl_add_u64 v[212:213], v[214:215], 0, s[50:51]
	s_addc_u32 s29, s29, 0
	s_add_i32 s30, s61, s35
	global_load_lds_dwordx4 v[212:213], off
	v_lshl_add_u64 v[212:213], s[28:29], 0, v[150:151]
	s_mov_b32 m0, s30
	s_nop 0
	global_load_lds_dwordx4 v[212:213], off
	v_lshl_add_u64 v[212:213], s[28:29], 0, v[154:155]
	s_add_i32 m0, s30, 0x2000
	s_nop 0
	global_load_lds_dwordx4 v[212:213], off
	v_lshl_add_u64 v[212:213], v[216:217], 0, s[50:51]
	s_mov_b32 m0, s41
	s_nop 0
	global_load_lds_dwordx4 v[212:213], off
	v_lshl_add_u64 v[212:213], v[220:221], 0, s[50:51]
	s_mov_b32 m0, s42
	s_nop 0
	global_load_lds_dwordx4 v[212:213], off
	s_waitcnt vmcnt(8)
	s_waitcnt lgkmcnt(0)
	s_setprio 1
	s_barrier
	v_mfma_f32_16x16x32_bf16 v[82:85], v[54:57], v[180:183], v[82:85]
	v_mfma_f32_16x16x32_bf16 v[78:81], v[70:73], v[180:183], v[78:81]
	v_mfma_f32_16x16x32_bf16 v[66:69], v[54:57], v[188:191], v[66:69]
	v_mfma_f32_16x16x32_bf16 v[62:65], v[70:73], v[188:191], v[62:65]
	v_mfma_f32_16x16x32_bf16 v[34:37], v[54:57], v[196:199], v[34:37]
	v_mfma_f32_16x16x32_bf16 v[30:33], v[70:73], v[196:199], v[30:33]
	v_mfma_f32_16x16x32_bf16 v[18:21], v[54:57], v[204:207], v[18:21]
	v_mfma_f32_16x16x32_bf16 v[14:17], v[70:73], v[204:207], v[14:17]
	v_mfma_f32_16x16x32_bf16 v[82:85], v[58:61], v[184:187], v[82:85]
	v_mfma_f32_16x16x32_bf16 v[78:81], v[74:77], v[184:187], v[78:81]
	v_mfma_f32_16x16x32_bf16 v[66:69], v[58:61], v[192:195], v[66:69]
	v_mfma_f32_16x16x32_bf16 v[62:65], v[74:77], v[192:195], v[62:65]
	v_mfma_f32_16x16x32_bf16 v[34:37], v[58:61], v[200:203], v[34:37]
	v_mfma_f32_16x16x32_bf16 v[30:33], v[74:77], v[200:203], v[30:33]
	v_mfma_f32_16x16x32_bf16 v[18:21], v[58:61], v[208:211], v[18:21]
	v_mfma_f32_16x16x32_bf16 v[14:17], v[74:77], v[208:211], v[14:17]
	s_setprio 0
	s_setprio 1
	v_mfma_f32_16x16x32_bf16 v[46:49], v[160:163], v[180:183], v[46:49]
	v_mfma_f32_16x16x32_bf16 v[74:77], v[168:171], v[184:187], v[46:49]
	v_mfma_f32_16x16x32_bf16 v[46:49], v[172:175], v[180:183], v[50:53]
	v_mfma_f32_16x16x32_bf16 v[42:45], v[160:163], v[188:191], v[42:45]
	v_mfma_f32_16x16x32_bf16 v[38:41], v[172:175], v[188:191], v[38:41]
	v_mfma_f32_16x16x32_bf16 v[26:29], v[160:163], v[196:199], v[26:29]
	v_mfma_f32_16x16x32_bf16 v[22:25], v[172:175], v[196:199], v[22:25]
	v_mfma_f32_16x16x32_bf16 v[10:13], v[160:163], v[204:207], v[10:13]
	v_mfma_f32_16x16x32_bf16 v[6:9], v[172:175], v[204:207], v[6:9]
	v_mfma_f32_16x16x32_bf16 v[70:73], v[176:179], v[184:187], v[46:49]
	v_mfma_f32_16x16x32_bf16 v[42:45], v[168:171], v[192:195], v[42:45]
	v_mfma_f32_16x16x32_bf16 v[38:41], v[176:179], v[192:195], v[38:41]
	v_mfma_f32_16x16x32_bf16 v[26:29], v[168:171], v[200:203], v[26:29]
	v_mfma_f32_16x16x32_bf16 v[22:25], v[176:179], v[200:203], v[22:25]
	v_mfma_f32_16x16x32_bf16 v[10:13], v[168:171], v[208:211], v[10:13]
	v_mfma_f32_16x16x32_bf16 v[6:9], v[176:179], v[208:211], v[6:9]
	s_barrier
	s_setprio 0
	s_add_i32 s59, s59, 2
	s_add_u32 s26, s26, 0x100
	s_addc_u32 s27, s27, 0
	s_add_u32 s48, s48, 0x100
	s_addc_u32 s58, s58, 0
	s_cmp_gt_u32 s59, 13
	s_cbranch_scc0 .LBB0_205
	s_and_b64 vcc, exec, s[14:15]
	s_cbranch_vccz .LBB0_208
	s_barrier

.LBB0_301:
	s_add_i32 s80, s38, 2
	s_add_u32 s81, s36, 0x80
	s_addc_u32 s39, s37, 0
	s_add_i32 s84, 0, 0x10000
	s_cmp_eq_u32 s31, s38
	s_cselect_b32 s39, s27, s39
	s_cselect_b32 s38, s26, s81
	s_waitcnt lgkmcnt(0)
	s_cselect_b32 s83, s29, s79
	s_cselect_b32 s82, s28, s78
	s_add_i32 s81, 0, 0x14000
	v_add_u32_e32 v146, s84, v206
	v_add_u32_e32 v162, s81, v206
	ds_read_b128 v[134:137], v146
	ds_read_b128 v[138:141], v146 offset:1024
	ds_read_b128 v[142:145], v146 offset:2048
	ds_read_b128 v[146:149], v146 offset:3072
	ds_read_b128 v[150:153], v162
	ds_read_b128 v[154:157], v162 offset:1024
	ds_read_b128 v[158:161], v162 offset:2048
	ds_read_b128 v[162:165], v162 offset:3072
	v_lshl_add_u64 v[202:203], s[36:37], 0, v[182:183]
	s_add_i32 m0, s44, 0xc000
	ds_read_b128 v[166:169], v209
	ds_read_b128 v[170:173], v209 offset:1024
	ds_read_b128 v[174:177], v209 offset:2048
	ds_read_b128 v[178:181], v209 offset:3072
	ds_read_b128 v[186:189], v209 offset:4096
	ds_read_b128 v[190:193], v209 offset:5120
	ds_read_b128 v[194:197], v209 offset:6144
	ds_read_b128 v[198:201], v209 offset:7168
	global_load_lds_dwordx4 v[202:203], off
	v_lshl_add_u64 v[202:203], s[36:37], 0, v[184:185]
	s_add_i32 m0, s44, 0xe000
	s_nop 0
	global_load_lds_dwordx4 v[202:203], off
	s_waitcnt vmcnt(8)
	s_waitcnt lgkmcnt(0)
	s_setprio 1
	s_barrier
	v_mfma_f32_16x16x32_bf16 v[130:133], v[134:137], v[166:169], v[130:133]
	v_mfma_f32_16x16x32_bf16 v[126:129], v[142:145], v[166:169], v[126:129]
	v_mfma_f32_16x16x32_bf16 v[114:117], v[134:137], v[174:177], v[114:117]
	v_mfma_f32_16x16x32_bf16 v[110:113], v[142:145], v[174:177], v[110:113]
	v_mfma_f32_16x16x32_bf16 v[98:101], v[134:137], v[186:189], v[98:101]
	v_mfma_f32_16x16x32_bf16 v[94:97], v[142:145], v[186:189], v[94:97]
	v_mfma_f32_16x16x32_bf16 v[82:85], v[134:137], v[194:197], v[82:85]
	v_mfma_f32_16x16x32_bf16 v[78:81], v[142:145], v[194:197], v[78:81]
	v_mfma_f32_16x16x32_bf16 v[130:133], v[138:141], v[170:173], v[130:133]
	v_mfma_f32_16x16x32_bf16 v[126:129], v[146:149], v[170:173], v[126:129]
	v_mfma_f32_16x16x32_bf16 v[114:117], v[138:141], v[178:181], v[114:117]
	v_mfma_f32_16x16x32_bf16 v[110:113], v[146:149], v[178:181], v[110:113]
	v_mfma_f32_16x16x32_bf16 v[98:101], v[138:141], v[190:193], v[98:101]
	v_mfma_f32_16x16x32_bf16 v[94:97], v[146:149], v[190:193], v[94:97]
	v_mfma_f32_16x16x32_bf16 v[82:85], v[138:141], v[198:201], v[82:85]
	v_mfma_f32_16x16x32_bf16 v[78:81], v[146:149], v[198:201], v[78:81]
	s_setprio 0
	s_setprio 1
	v_mfma_f32_16x16x32_bf16 v[122:125], v[150:153], v[166:169], v[122:125]
	v_mfma_f32_16x16x32_bf16 v[118:121], v[158:161], v[166:169], v[118:121]
	v_mfma_f32_16x16x32_bf16 v[106:109], v[150:153], v[174:177], v[106:109]
	v_mfma_f32_16x16x32_bf16 v[102:105], v[158:161], v[174:177], v[102:105]
	v_mfma_f32_16x16x32_bf16 v[90:93], v[150:153], v[186:189], v[90:93]
	v_mfma_f32_16x16x32_bf16 v[86:89], v[158:161], v[186:189], v[86:89]
	v_mfma_f32_16x16x32_bf16 v[74:77], v[150:153], v[194:197], v[74:77]
	v_mfma_f32_16x16x32_bf16 v[70:73], v[158:161], v[194:197], v[70:73]
	v_mfma_f32_16x16x32_bf16 v[122:125], v[154:157], v[170:173], v[122:125]
	v_mfma_f32_16x16x32_bf16 v[118:121], v[162:165], v[170:173], v[118:121]
	v_mfma_f32_16x16x32_bf16 v[106:109], v[154:157], v[178:181], v[106:109]
	v_mfma_f32_16x16x32_bf16 v[102:105], v[162:165], v[178:181], v[102:105]
	v_mfma_f32_16x16x32_bf16 v[90:93], v[154:157], v[190:193], v[90:93]
	v_mfma_f32_16x16x32_bf16 v[86:89], v[162:165], v[190:193], v[86:89]
	v_mfma_f32_16x16x32_bf16 v[74:77], v[154:157], v[198:201], v[74:77]
	v_mfma_f32_16x16x32_bf16 v[70:73], v[162:165], v[198:201], v[70:73]
	s_barrier
	s_setprio 0
	s_add_i32 s84, s84, s43
	v_lshl_add_u64 v[202:203], s[82:83], 0, v[0:1]
	s_mov_b32 m0, s84
	ds_read_b128 v[166:169], v209 offset:16384
	ds_read_b128 v[170:173], v209 offset:17408
	ds_read_b128 v[174:177], v209 offset:18432
	ds_read_b128 v[178:181], v209 offset:19456
	ds_read_b128 v[186:189], v209 offset:20480
	ds_read_b128 v[190:193], v209 offset:21504
	ds_read_b128 v[194:197], v209 offset:22528
	ds_read_b128 v[198:201], v209 offset:23552
	global_load_lds_dwordx4 v[202:203], off
	s_add_i32 m0, s84, 0x2000
	v_lshl_add_u64 v[204:205], s[82:83], 0, v[2:3]
	s_add_u32 s82, s82, s48
	s_addc_u32 s83, s83, 0
	s_add_i32 s81, s81, s43
	global_load_lds_dwordx4 v[204:205], off
	v_lshl_add_u64 v[210:211], s[82:83], 0, v[0:1]
	s_mov_b32 m0, s81
	v_lshl_add_u64 v[212:213], s[82:83], 0, v[2:3]
	global_load_lds_dwordx4 v[210:211], off
	s_add_i32 m0, s81, 0x2000
	v_lshl_add_u64 v[214:215], s[38:39], 0, v[0:1]
	global_load_lds_dwordx4 v[212:213], off
	s_mov_b32 m0, s44
	v_lshl_add_u64 v[216:217], s[38:39], 0, v[2:3]
	global_load_lds_dwordx4 v[214:215], off
	s_mov_b32 m0, s45
	s_nop 0
	global_load_lds_dwordx4 v[216:217], off
	s_waitcnt vmcnt(8)
	s_waitcnt lgkmcnt(0)
	s_setprio 1
	s_barrier
	v_mfma_f32_16x16x32_bf16 v[66:69], v[134:137], v[166:169], v[66:69]
	v_mfma_f32_16x16x32_bf16 v[62:65], v[142:145], v[166:169], v[62:65]
	v_mfma_f32_16x16x32_bf16 v[50:53], v[134:137], v[174:177], v[50:53]
	v_mfma_f32_16x16x32_bf16 v[46:49], v[142:145], v[174:177], v[46:49]
	v_mfma_f32_16x16x32_bf16 v[34:37], v[134:137], v[186:189], v[34:37]
	v_mfma_f32_16x16x32_bf16 v[30:33], v[142:145], v[186:189], v[30:33]
	v_mfma_f32_16x16x32_bf16 v[18:21], v[134:137], v[194:197], v[18:21]
	v_mfma_f32_16x16x32_bf16 v[14:17], v[142:145], v[194:197], v[14:17]
	v_mfma_f32_16x16x32_bf16 v[66:69], v[138:141], v[170:173], v[66:69]
	v_mfma_f32_16x16x32_bf16 v[62:65], v[146:149], v[170:173], v[62:65]
	v_mfma_f32_16x16x32_bf16 v[50:53], v[138:141], v[178:181], v[50:53]
	v_mfma_f32_16x16x32_bf16 v[46:49], v[146:149], v[178:181], v[46:49]
	v_mfma_f32_16x16x32_bf16 v[34:37], v[138:141], v[190:193], v[34:37]
	v_mfma_f32_16x16x32_bf16 v[30:33], v[146:149], v[190:193], v[30:33]
	v_mfma_f32_16x16x32_bf16 v[18:21], v[138:141], v[198:201], v[18:21]
	v_mfma_f32_16x16x32_bf16 v[14:17], v[146:149], v[198:201], v[14:17]
	s_setprio 0
	s_setprio 1
	v_mfma_f32_16x16x32_bf16 v[58:61], v[150:153], v[166:169], v[58:61]
	v_mfma_f32_16x16x32_bf16 v[54:57], v[158:161], v[166:169], v[54:57]
	v_mfma_f32_16x16x32_bf16 v[42:45], v[150:153], v[174:177], v[42:45]
	v_mfma_f32_16x16x32_bf16 v[38:41], v[158:161], v[174:177], v[38:41]
	v_mfma_f32_16x16x32_bf16 v[26:29], v[150:153], v[186:189], v[26:29]
	v_mfma_f32_16x16x32_bf16 v[22:25], v[158:161], v[186:189], v[22:25]
	v_mfma_f32_16x16x32_bf16 v[10:13], v[150:153], v[194:197], v[10:13]
	v_mfma_f32_16x16x32_bf16 v[6:9], v[158:161], v[194:197], v[6:9]
	v_mfma_f32_16x16x32_bf16 v[58:61], v[154:157], v[170:173], v[58:61]
	v_mfma_f32_16x16x32_bf16 v[54:57], v[162:165], v[170:173], v[54:57]
	v_mfma_f32_16x16x32_bf16 v[42:45], v[154:157], v[178:181], v[42:45]
	v_mfma_f32_16x16x32_bf16 v[38:41], v[162:165], v[178:181], v[38:41]
	v_mfma_f32_16x16x32_bf16 v[26:29], v[154:157], v[190:193], v[26:29]
	v_mfma_f32_16x16x32_bf16 v[22:25], v[162:165], v[190:193], v[22:25]
	v_mfma_f32_16x16x32_bf16 v[10:13], v[154:157], v[198:201], v[10:13]
	v_mfma_f32_16x16x32_bf16 v[6:9], v[162:165], v[198:201], v[6:9]
	s_barrier
	s_setprio 0
	s_add_i32 s81, 0, 0x18000
	s_add_i32 s82, 0, 0x1c000
	v_add_u32_e32 v146, s81, v206
	v_add_u32_e32 v162, s82, v206
	ds_read_b128 v[134:137], v146
	ds_read_b128 v[138:141], v146 offset:1024
	ds_read_b128 v[142:145], v146 offset:2048
	ds_read_b128 v[146:149], v146 offset:3072
	ds_read_b128 v[150:153], v162
	ds_read_b128 v[154:157], v162 offset:1024
	ds_read_b128 v[158:161], v162 offset:2048
	ds_read_b128 v[162:165], v162 offset:3072
	s_add_u32 s38, s38, s48
	s_addc_u32 s39, s39, 0
	s_mov_b32 m0, s58
	v_lshl_add_u64 v[220:221], s[38:39], 0, v[0:1]
	ds_read_b128 v[166:169], v209 offset:32768
	ds_read_b128 v[170:173], v209 offset:33792
	ds_read_b128 v[174:177], v209 offset:34816
	ds_read_b128 v[178:181], v209 offset:35840
	ds_read_b128 v[186:189], v209 offset:36864
	ds_read_b128 v[190:193], v209 offset:37888
	ds_read_b128 v[194:197], v209 offset:38912
	ds_read_b128 v[198:201], v209 offset:39936
	global_load_lds_dwordx4 v[220:221], off
	v_lshl_add_u64 v[220:221], s[38:39], 0, v[2:3]
	s_mov_b32 m0, s59
	s_nop 0
	global_load_lds_dwordx4 v[220:221], off
	s_waitcnt vmcnt(8)
	s_waitcnt lgkmcnt(0)
	s_setprio 1
	s_barrier
	v_mfma_f32_16x16x32_bf16 v[130:133], v[134:137], v[166:169], v[130:133]
	v_mfma_f32_16x16x32_bf16 v[126:129], v[142:145], v[166:169], v[126:129]
	v_mfma_f32_16x16x32_bf16 v[114:117], v[134:137], v[174:177], v[114:117]
	v_mfma_f32_16x16x32_bf16 v[110:113], v[142:145], v[174:177], v[110:113]
	v_mfma_f32_16x16x32_bf16 v[98:101], v[134:137], v[186:189], v[98:101]
	v_mfma_f32_16x16x32_bf16 v[94:97], v[142:145], v[186:189], v[94:97]
	v_mfma_f32_16x16x32_bf16 v[82:85], v[134:137], v[194:197], v[82:85]
	v_mfma_f32_16x16x32_bf16 v[78:81], v[142:145], v[194:197], v[78:81]
	v_mfma_f32_16x16x32_bf16 v[130:133], v[138:141], v[170:173], v[130:133]
	v_mfma_f32_16x16x32_bf16 v[126:129], v[146:149], v[170:173], v[126:129]
	v_mfma_f32_16x16x32_bf16 v[114:117], v[138:141], v[178:181], v[114:117]
	v_mfma_f32_16x16x32_bf16 v[110:113], v[146:149], v[178:181], v[110:113]
	v_mfma_f32_16x16x32_bf16 v[98:101], v[138:141], v[190:193], v[98:101]
	v_mfma_f32_16x16x32_bf16 v[94:97], v[146:149], v[190:193], v[94:97]
	v_mfma_f32_16x16x32_bf16 v[82:85], v[138:141], v[198:201], v[82:85]
	v_mfma_f32_16x16x32_bf16 v[78:81], v[146:149], v[198:201], v[78:81]
	s_setprio 0
	s_setprio 1
	v_mfma_f32_16x16x32_bf16 v[122:125], v[150:153], v[166:169], v[122:125]
	v_mfma_f32_16x16x32_bf16 v[118:121], v[158:161], v[166:169], v[118:121]
	v_mfma_f32_16x16x32_bf16 v[106:109], v[150:153], v[174:177], v[106:109]
	v_mfma_f32_16x16x32_bf16 v[102:105], v[158:161], v[174:177], v[102:105]
	v_mfma_f32_16x16x32_bf16 v[90:93], v[150:153], v[186:189], v[90:93]
	v_mfma_f32_16x16x32_bf16 v[86:89], v[158:161], v[186:189], v[86:89]
	v_mfma_f32_16x16x32_bf16 v[74:77], v[150:153], v[194:197], v[74:77]
	v_mfma_f32_16x16x32_bf16 v[70:73], v[158:161], v[194:197], v[70:73]
	v_mfma_f32_16x16x32_bf16 v[122:125], v[154:157], v[170:173], v[122:125]
	v_mfma_f32_16x16x32_bf16 v[118:121], v[162:165], v[170:173], v[118:121]
	v_mfma_f32_16x16x32_bf16 v[106:109], v[154:157], v[178:181], v[106:109]
	v_mfma_f32_16x16x32_bf16 v[102:105], v[162:165], v[178:181], v[102:105]
	v_mfma_f32_16x16x32_bf16 v[90:93], v[154:157], v[190:193], v[90:93]
	v_mfma_f32_16x16x32_bf16 v[86:89], v[162:165], v[190:193], v[86:89]
	v_mfma_f32_16x16x32_bf16 v[74:77], v[154:157], v[198:201], v[74:77]
	v_mfma_f32_16x16x32_bf16 v[70:73], v[162:165], v[198:201], v[70:73]
	s_barrier
	s_setprio 0
	s_add_i32 s38, s81, s43
	v_lshl_add_u64 v[202:203], v[202:203], 0, s[50:51]
	s_mov_b32 m0, s38
	ds_read_b128 v[166:169], v209 offset:49152
	ds_read_b128 v[170:173], v209 offset:50176
	ds_read_b128 v[174:177], v209 offset:51200
	ds_read_b128 v[178:181], v209 offset:52224
	ds_read_b128 v[186:189], v209 offset:53248
	ds_read_b128 v[190:193], v209 offset:54272
	ds_read_b128 v[194:197], v209 offset:55296
	ds_read_b128 v[198:201], v209 offset:56320
	global_load_lds_dwordx4 v[202:203], off
	v_lshl_add_u64 v[202:203], v[204:205], 0, s[50:51]
	s_add_i32 m0, s38, 0x2000
	s_add_i32 s38, s82, s43
	global_load_lds_dwordx4 v[202:203], off
	v_lshl_add_u64 v[202:203], v[210:211], 0, s[50:51]
	s_mov_b32 m0, s38
	s_nop 0
	global_load_lds_dwordx4 v[202:203], off
	v_lshl_add_u64 v[202:203], v[212:213], 0, s[50:51]
	s_add_i32 m0, s38, 0x2000
	s_nop 0
	global_load_lds_dwordx4 v[202:203], off
	v_lshl_add_u64 v[202:203], v[214:215], 0, s[50:51]
	s_mov_b32 m0, s63
	s_nop 0
	global_load_lds_dwordx4 v[202:203], off
	v_lshl_add_u64 v[202:203], v[216:217], 0, s[50:51]
	s_mov_b32 m0, s64
	s_nop 0
	global_load_lds_dwordx4 v[202:203], off
	s_waitcnt vmcnt(8)
	s_waitcnt lgkmcnt(0)
	s_setprio 1
	s_barrier
	v_mfma_f32_16x16x32_bf16 v[66:69], v[134:137], v[166:169], v[66:69]
	v_mfma_f32_16x16x32_bf16 v[62:65], v[142:145], v[166:169], v[62:65]
	v_mfma_f32_16x16x32_bf16 v[50:53], v[134:137], v[174:177], v[50:53]
	v_mfma_f32_16x16x32_bf16 v[46:49], v[142:145], v[174:177], v[46:49]
	v_mfma_f32_16x16x32_bf16 v[34:37], v[134:137], v[186:189], v[34:37]
	v_mfma_f32_16x16x32_bf16 v[30:33], v[142:145], v[186:189], v[30:33]
	v_mfma_f32_16x16x32_bf16 v[18:21], v[134:137], v[194:197], v[18:21]
	v_mfma_f32_16x16x32_bf16 v[14:17], v[142:145], v[194:197], v[14:17]
	v_mfma_f32_16x16x32_bf16 v[66:69], v[138:141], v[170:173], v[66:69]
	v_mfma_f32_16x16x32_bf16 v[62:65], v[146:149], v[170:173], v[62:65]
	v_mfma_f32_16x16x32_bf16 v[50:53], v[138:141], v[178:181], v[50:53]
	v_mfma_f32_16x16x32_bf16 v[46:49], v[146:149], v[178:181], v[46:49]
	v_mfma_f32_16x16x32_bf16 v[34:37], v[138:141], v[190:193], v[34:37]
	v_mfma_f32_16x16x32_bf16 v[30:33], v[146:149], v[190:193], v[30:33]
	v_mfma_f32_16x16x32_bf16 v[18:21], v[138:141], v[198:201], v[18:21]
	v_mfma_f32_16x16x32_bf16 v[14:17], v[146:149], v[198:201], v[14:17]
	s_setprio 0
	s_setprio 1
	v_mfma_f32_16x16x32_bf16 v[58:61], v[150:153], v[166:169], v[58:61]
	v_mfma_f32_16x16x32_bf16 v[54:57], v[158:161], v[166:169], v[54:57]
	v_mfma_f32_16x16x32_bf16 v[42:45], v[150:153], v[174:177], v[42:45]
	v_mfma_f32_16x16x32_bf16 v[38:41], v[158:161], v[174:177], v[38:41]
	v_mfma_f32_16x16x32_bf16 v[26:29], v[150:153], v[186:189], v[26:29]
	v_mfma_f32_16x16x32_bf16 v[22:25], v[158:161], v[186:189], v[22:25]
	v_mfma_f32_16x16x32_bf16 v[10:13], v[150:153], v[194:197], v[10:13]
	v_mfma_f32_16x16x32_bf16 v[6:9], v[158:161], v[194:197], v[6:9]
	v_mfma_f32_16x16x32_bf16 v[58:61], v[154:157], v[170:173], v[58:61]
	v_mfma_f32_16x16x32_bf16 v[54:57], v[162:165], v[170:173], v[54:57]
	v_mfma_f32_16x16x32_bf16 v[42:45], v[154:157], v[178:181], v[42:45]
	v_mfma_f32_16x16x32_bf16 v[38:41], v[162:165], v[178:181], v[38:41]
	v_mfma_f32_16x16x32_bf16 v[26:29], v[154:157], v[190:193], v[26:29]
	v_mfma_f32_16x16x32_bf16 v[22:25], v[162:165], v[190:193], v[22:25]
	v_mfma_f32_16x16x32_bf16 v[10:13], v[154:157], v[198:201], v[10:13]
	v_mfma_f32_16x16x32_bf16 v[6:9], v[162:165], v[198:201], v[6:9]
	s_barrier
	s_setprio 0
	s_add_u32 s36, s36, 0x100
	s_addc_u32 s37, s37, 0
	s_add_u32 s78, s78, 0x100
	s_addc_u32 s79, s79, 0
	s_cmp_ge_i32 s80, s25
	s_mov_b32 s38, s80
	s_cbranch_scc0 .LBB0_301
	s_load_dwordx2 s[82:83], s[54:55], 0xe0
	v_readlane_b32 s80, v253, 39
	v_readlane_b32 s84, v253, 44
	v_readlane_b32 s81, v253, 40
	s_and_b64 vcc, exec, s[20:21]
	s_cbranch_vccz .LBB0_304

.LBB0_347:
	s_add_u32 s34, s8, 0xfffc0080
	s_addc_u32 s35, s9, -1
	s_add_i32 s41, 0, 0x10000
	s_cmp_eq_u32 s39, 12
	s_cselect_b32 s37, s3, s35
	s_cselect_b32 s36, s7, s34
	v_add_u32_e32 v0, s41, v243
	s_cselect_b32 s35, s25, s38
	s_cselect_b32 s34, s27, s33
	s_add_i32 s44, 0, 0x14000
	ds_read_b128 v[40:43], v0
	ds_read_b128 v[44:47], v0 offset:1024
	ds_read_b128 v[48:51], v0 offset:2048
	ds_read_b128 v[52:55], v0 offset:3072
	v_add_u32_e32 v0, s44, v243
	s_waitcnt vmcnt(0)
	ds_read_b128 v[64:67], v0
	ds_read_b128 v[68:71], v0 offset:1024
	ds_read_b128 v[80:83], v0 offset:2048
	ds_read_b128 v[84:87], v0 offset:3072
	v_lshl_add_u64 v[2:3], s[8:9], 0, v[198:199]
	s_add_i32 m0, s61, 0xc000
	ds_read_b128 v[88:91], v244
	ds_read_b128 v[92:95], v244 offset:1024
	ds_read_b128 v[176:179], v244 offset:2048
	ds_read_b128 v[180:183], v244 offset:3072
	ds_read_b128 v[202:205], v244 offset:4096
	ds_read_b128 v[206:209], v244 offset:5120
	ds_read_b128 v[210:213], v244 offset:6144
	ds_read_b128 v[220:223], v244 offset:7168
	global_load_lds_dwordx4 v[2:3], off
	v_lshl_add_u64 v[2:3], s[8:9], 0, v[200:201]
	s_add_i32 m0, s61, 0xe000
	s_nop 0
	global_load_lds_dwordx4 v[2:3], off
	s_waitcnt vmcnt(8)
	s_waitcnt lgkmcnt(0)
	s_setprio 1
	s_barrier
	v_mfma_f32_16x16x32_bf16 v[172:175], v[40:43], v[88:91], v[172:175]
	v_mfma_f32_16x16x32_bf16 v[168:171], v[48:51], v[88:91], v[168:171]
	v_mfma_f32_16x16x32_bf16 v[156:159], v[40:43], v[176:179], v[156:159]
	v_mfma_f32_16x16x32_bf16 v[152:155], v[48:51], v[176:179], v[152:155]
	v_mfma_f32_16x16x32_bf16 v[140:143], v[40:43], v[202:205], v[140:143]
	v_mfma_f32_16x16x32_bf16 v[136:139], v[48:51], v[202:205], v[136:139]
	v_mfma_f32_16x16x32_bf16 v[124:127], v[40:43], v[210:213], v[124:127]
	v_mfma_f32_16x16x32_bf16 v[120:123], v[48:51], v[210:213], v[120:123]
	v_mfma_f32_16x16x32_bf16 v[172:175], v[44:47], v[92:95], v[172:175]
	v_mfma_f32_16x16x32_bf16 v[168:171], v[52:55], v[92:95], v[168:171]
	v_mfma_f32_16x16x32_bf16 v[156:159], v[44:47], v[180:183], v[156:159]
	v_mfma_f32_16x16x32_bf16 v[152:155], v[52:55], v[180:183], v[152:155]
	v_mfma_f32_16x16x32_bf16 v[140:143], v[44:47], v[206:209], v[140:143]
	v_mfma_f32_16x16x32_bf16 v[136:139], v[52:55], v[206:209], v[136:139]
	v_mfma_f32_16x16x32_bf16 v[124:127], v[44:47], v[220:223], v[124:127]
	v_mfma_f32_16x16x32_bf16 v[120:123], v[52:55], v[220:223], v[120:123]
	s_setprio 0
	s_setprio 1
	v_mfma_f32_16x16x32_bf16 v[164:167], v[64:67], v[88:91], v[164:167]
	v_mfma_f32_16x16x32_bf16 v[88:91], v[80:83], v[88:91], v[160:163]
	v_mfma_f32_16x16x32_bf16 v[144:147], v[80:83], v[176:179], v[144:147]
	v_mfma_f32_16x16x32_bf16 v[132:135], v[64:67], v[202:205], v[132:135]
	v_mfma_f32_16x16x32_bf16 v[128:131], v[80:83], v[202:205], v[128:131]
	v_mfma_f32_16x16x32_bf16 v[116:119], v[64:67], v[210:213], v[116:119]
	v_mfma_f32_16x16x32_bf16 v[112:115], v[80:83], v[210:213], v[112:115]
	v_mfma_f32_16x16x32_bf16 v[164:167], v[68:71], v[92:95], v[164:167]
	v_mfma_f32_16x16x32_bf16 v[88:91], v[84:87], v[92:95], v[88:91]
	v_mfma_f32_16x16x32_bf16 v[92:95], v[64:67], v[176:179], v[148:151]
	v_mfma_f32_16x16x32_bf16 v[144:147], v[84:87], v[180:183], v[144:147]
	v_mfma_f32_16x16x32_bf16 v[132:135], v[68:71], v[206:209], v[132:135]
	v_mfma_f32_16x16x32_bf16 v[128:131], v[84:87], v[206:209], v[128:131]
	v_mfma_f32_16x16x32_bf16 v[116:119], v[68:71], v[220:223], v[116:119]
	v_mfma_f32_16x16x32_bf16 v[112:115], v[84:87], v[220:223], v[112:115]
	v_mfma_f32_16x16x32_bf16 v[92:95], v[68:71], v[180:183], v[92:95]
	s_barrier
	s_setprio 0
	s_add_i32 s41, s41, s60
	v_lshl_add_u64 v[2:3], s[34:35], 0, v[186:187]
	s_mov_b32 m0, s41
	ds_read_b128 v[148:151], v244 offset:16384
	ds_read_b128 v[160:163], v244 offset:17408
	ds_read_b128 v[176:179], v244 offset:18432
	ds_read_b128 v[180:183], v244 offset:19456
	ds_read_b128 v[202:205], v244 offset:20480
	ds_read_b128 v[206:209], v244 offset:21504
	ds_read_b128 v[210:213], v244 offset:22528
	ds_read_b128 v[220:223], v244 offset:23552
	global_load_lds_dwordx4 v[2:3], off
	s_add_i32 m0, s41, 0x2000
	s_add_u32 s42, s34, 0x40000
	v_lshl_add_u64 v[214:215], s[34:35], 0, v[190:191]
	s_addc_u32 s43, s35, 0
	s_add_i32 s41, s44, s60
	global_load_lds_dwordx4 v[214:215], off
	v_lshl_add_u64 v[6:7], s[42:43], 0, v[186:187]
	s_mov_b32 m0, s41
	v_lshl_add_u64 v[216:217], s[36:37], 0, v[184:185]
	global_load_lds_dwordx4 v[6:7], off
	v_lshl_add_u64 v[6:7], s[42:43], 0, v[190:191]
	s_add_i32 m0, s41, 0x2000
	v_lshl_add_u64 v[228:229], s[36:37], 0, v[188:189]
	global_load_lds_dwordx4 v[6:7], off
	s_mov_b32 m0, s61
	s_nop 0
	global_load_lds_dwordx4 v[216:217], off
	s_mov_b32 m0, s62
	s_nop 0
	global_load_lds_dwordx4 v[228:229], off
	s_waitcnt vmcnt(8)
	s_waitcnt lgkmcnt(0)
	s_setprio 1
	s_barrier
	v_mfma_f32_16x16x32_bf16 v[108:111], v[40:43], v[148:151], v[108:111]
	v_mfma_f32_16x16x32_bf16 v[104:107], v[48:51], v[148:151], v[104:107]
	v_mfma_f32_16x16x32_bf16 v[76:79], v[40:43], v[176:179], v[76:79]
	v_mfma_f32_16x16x32_bf16 v[72:75], v[48:51], v[176:179], v[72:75]
	v_mfma_f32_16x16x32_bf16 v[36:39], v[40:43], v[202:205], v[36:39]
	v_mfma_f32_16x16x32_bf16 v[32:35], v[48:51], v[202:205], v[32:35]
	v_mfma_f32_16x16x32_bf16 v[20:23], v[40:43], v[210:213], v[20:23]
	v_mfma_f32_16x16x32_bf16 v[16:19], v[48:51], v[210:213], v[16:19]
	v_mfma_f32_16x16x32_bf16 v[108:111], v[44:47], v[160:163], v[108:111]
	v_mfma_f32_16x16x32_bf16 v[104:107], v[52:55], v[160:163], v[104:107]
	v_mfma_f32_16x16x32_bf16 v[76:79], v[44:47], v[180:183], v[76:79]
	v_mfma_f32_16x16x32_bf16 v[72:75], v[52:55], v[180:183], v[72:75]
	v_mfma_f32_16x16x32_bf16 v[36:39], v[44:47], v[206:209], v[36:39]
	v_mfma_f32_16x16x32_bf16 v[32:35], v[52:55], v[206:209], v[32:35]
	v_mfma_f32_16x16x32_bf16 v[20:23], v[44:47], v[220:223], v[20:23]
	v_mfma_f32_16x16x32_bf16 v[16:19], v[52:55], v[220:223], v[16:19]
	s_setprio 0
	s_setprio 1
	v_mfma_f32_16x16x32_bf16 v[28:31], v[64:67], v[202:205], v[28:31]
	v_mfma_f32_16x16x32_bf16 v[24:27], v[80:83], v[202:205], v[24:27]
	v_mfma_f32_16x16x32_bf16 v[12:15], v[64:67], v[210:213], v[12:15]
	v_mfma_f32_16x16x32_bf16 v[6:9], v[80:83], v[210:213], v[8:11]
	v_mfma_f32_16x16x32_bf16 v[40:43], v[64:67], v[148:151], v[100:103]
	v_mfma_f32_16x16x32_bf16 v[44:47], v[80:83], v[148:151], v[96:99]
	v_mfma_f32_16x16x32_bf16 v[48:51], v[64:67], v[176:179], v[60:63]
	v_mfma_f32_16x16x32_bf16 v[52:55], v[80:83], v[176:179], v[56:59]
	v_mfma_f32_16x16x32_bf16 v[28:31], v[68:71], v[206:209], v[28:31]
	v_mfma_f32_16x16x32_bf16 v[24:27], v[84:87], v[206:209], v[24:27]
	v_mfma_f32_16x16x32_bf16 v[12:15], v[68:71], v[220:223], v[12:15]
	v_mfma_f32_16x16x32_bf16 v[6:9], v[84:87], v[220:223], v[6:9]
	v_mfma_f32_16x16x32_bf16 v[40:43], v[68:71], v[160:163], v[40:43]
	v_mfma_f32_16x16x32_bf16 v[44:47], v[84:87], v[160:163], v[44:47]
	v_mfma_f32_16x16x32_bf16 v[48:51], v[68:71], v[180:183], v[48:51]
	v_mfma_f32_16x16x32_bf16 v[52:55], v[84:87], v[180:183], v[52:55]
	s_barrier
	s_setprio 0
	s_add_i32 s41, 0, 0x18000
	v_add_u32_e32 v0, s41, v243
	s_add_i32 s42, 0, 0x1c000
	ds_read_b128 v[56:59], v0
	ds_read_b128 v[60:63], v0 offset:1024
	ds_read_b128 v[64:67], v0 offset:2048
	ds_read_b128 v[68:71], v0 offset:3072
	v_add_u32_e32 v0, s42, v243
	ds_read_b128 v[80:83], v0
	ds_read_b128 v[84:87], v0 offset:1024
	ds_read_b128 v[176:179], v0 offset:2048
	ds_read_b128 v[180:183], v0 offset:3072
	s_add_u32 s36, s36, 0x40000
	s_addc_u32 s37, s37, 0
	s_mov_b32 m0, s63
	v_lshl_add_u64 v[10:11], s[36:37], 0, v[184:185]
	ds_read_b128 v[96:99], v244 offset:32768
	ds_read_b128 v[100:103], v244 offset:33792
	ds_read_b128 v[202:205], v244 offset:34816
	ds_read_b128 v[206:209], v244 offset:35840
	ds_read_b128 v[210:213], v244 offset:36864
	ds_read_b128 v[220:223], v244 offset:37888
	ds_read_b128 v[224:227], v244 offset:38912
	ds_read_b128 v[246:249], v244 offset:39936
	global_load_lds_dwordx4 v[10:11], off
	v_lshl_add_u64 v[10:11], s[36:37], 0, v[188:189]
	s_mov_b32 m0, s64
	s_nop 0
	global_load_lds_dwordx4 v[10:11], off
	s_waitcnt vmcnt(8)
	s_waitcnt lgkmcnt(0)
	s_setprio 1
	s_barrier
	v_mfma_f32_16x16x32_bf16 v[148:151], v[56:59], v[96:99], v[172:175]
	v_mfma_f32_16x16x32_bf16 v[172:175], v[60:63], v[100:103], v[148:151]
	v_mfma_f32_16x16x32_bf16 v[148:151], v[64:67], v[96:99], v[168:171]
	v_mfma_f32_16x16x32_bf16 v[168:171], v[68:71], v[100:103], v[148:151]
	v_mfma_f32_16x16x32_bf16 v[148:151], v[56:59], v[202:205], v[156:159]
	v_mfma_f32_16x16x32_bf16 v[156:159], v[60:63], v[206:209], v[148:151]
	v_mfma_f32_16x16x32_bf16 v[148:151], v[64:67], v[202:205], v[152:155]
	v_mfma_f32_16x16x32_bf16 v[140:143], v[56:59], v[210:213], v[140:143]
	v_mfma_f32_16x16x32_bf16 v[136:139], v[64:67], v[210:213], v[136:139]
	v_mfma_f32_16x16x32_bf16 v[124:127], v[56:59], v[224:227], v[124:127]
	v_mfma_f32_16x16x32_bf16 v[120:123], v[64:67], v[224:227], v[120:123]
	v_mfma_f32_16x16x32_bf16 v[152:155], v[68:71], v[206:209], v[148:151]
	v_mfma_f32_16x16x32_bf16 v[140:143], v[60:63], v[220:223], v[140:143]
	v_mfma_f32_16x16x32_bf16 v[136:139], v[68:71], v[220:223], v[136:139]
	v_mfma_f32_16x16x32_bf16 v[124:127], v[60:63], v[246:249], v[124:127]
	v_mfma_f32_16x16x32_bf16 v[120:123], v[68:71], v[246:249], v[120:123]
	s_setprio 0
	s_setprio 1
	v_mfma_f32_16x16x32_bf16 v[88:91], v[176:179], v[96:99], v[88:91]
	v_mfma_f32_16x16x32_bf16 v[148:151], v[80:83], v[96:99], v[164:167]
	v_mfma_f32_16x16x32_bf16 v[160:163], v[180:183], v[100:103], v[88:91]
	v_mfma_f32_16x16x32_bf16 v[88:91], v[80:83], v[202:205], v[92:95]
	v_mfma_f32_16x16x32_bf16 v[164:167], v[84:87], v[100:103], v[148:151]
	v_mfma_f32_16x16x32_bf16 v[148:151], v[84:87], v[206:209], v[88:91]
	v_mfma_f32_16x16x32_bf16 v[88:91], v[176:179], v[202:205], v[144:147]
	v_mfma_f32_16x16x32_bf16 v[144:147], v[180:183], v[206:209], v[88:91]
	v_mfma_f32_16x16x32_bf16 v[88:91], v[80:83], v[210:213], v[132:135]
	v_mfma_f32_16x16x32_bf16 v[132:135], v[84:87], v[220:223], v[88:91]
	v_mfma_f32_16x16x32_bf16 v[88:91], v[176:179], v[210:213], v[128:131]
	v_mfma_f32_16x16x32_bf16 v[128:131], v[180:183], v[220:223], v[88:91]
	v_mfma_f32_16x16x32_bf16 v[88:91], v[80:83], v[224:227], v[116:119]
	v_mfma_f32_16x16x32_bf16 v[116:119], v[84:87], v[246:249], v[88:91]
	v_mfma_f32_16x16x32_bf16 v[88:91], v[176:179], v[224:227], v[112:115]
	v_mfma_f32_16x16x32_bf16 v[112:115], v[180:183], v[246:249], v[88:91]
	s_barrier
	s_setprio 0
	s_add_i32 s36, s41, s60
	v_lshl_add_u64 v[2:3], v[2:3], 0, s[50:51]
	s_mov_b32 m0, s36
	s_nop 1
	ds_read_b128 v[88:91], v244 offset:49152
	ds_read_b128 v[92:95], v244 offset:50176
	ds_read_b128 v[202:205], v244 offset:51200
	ds_read_b128 v[206:209], v244 offset:52224
	ds_read_b128 v[210:213], v244 offset:53248
	ds_read_b128 v[220:223], v244 offset:54272
	ds_read_b128 v[224:227], v244 offset:55296
	ds_read_b128 v[246:249], v244 offset:56320
	global_load_lds_dwordx4 v[2:3], off
	s_add_i32 m0, s36, 0x2000
	s_add_u32 s34, s34, 0x40080
	v_lshl_add_u64 v[2:3], v[214:215], 0, s[50:51]
	s_addc_u32 s35, s35, 0
	s_add_i32 s36, s42, s60
	global_load_lds_dwordx4 v[2:3], off
	v_lshl_add_u64 v[2:3], s[34:35], 0, v[186:187]
	s_mov_b32 m0, s36
	s_nop 0
	global_load_lds_dwordx4 v[2:3], off
	v_lshl_add_u64 v[2:3], s[34:35], 0, v[190:191]
	s_add_i32 m0, s36, 0x2000
	s_nop 0
	global_load_lds_dwordx4 v[2:3], off
	v_lshl_add_u64 v[2:3], v[216:217], 0, s[50:51]
	s_mov_b32 m0, s74
	s_nop 0
	global_load_lds_dwordx4 v[2:3], off
	v_lshl_add_u64 v[2:3], v[228:229], 0, s[50:51]
	s_mov_b32 m0, s75
	s_nop 0
	global_load_lds_dwordx4 v[2:3], off
	s_waitcnt vmcnt(8)
	s_waitcnt lgkmcnt(0)
	s_setprio 1
	s_barrier
	v_mfma_f32_16x16x32_bf16 v[96:99], v[56:59], v[88:91], v[108:111]
	v_mfma_f32_16x16x32_bf16 v[108:111], v[60:63], v[92:95], v[96:99]
	v_mfma_f32_16x16x32_bf16 v[96:99], v[64:67], v[88:91], v[104:107]
	v_mfma_f32_16x16x32_bf16 v[76:79], v[56:59], v[202:205], v[76:79]
	v_mfma_f32_16x16x32_bf16 v[72:75], v[64:67], v[202:205], v[72:75]
	v_mfma_f32_16x16x32_bf16 v[36:39], v[56:59], v[210:213], v[36:39]
	v_mfma_f32_16x16x32_bf16 v[32:35], v[64:67], v[210:213], v[32:35]
	v_mfma_f32_16x16x32_bf16 v[20:23], v[56:59], v[224:227], v[20:23]
	v_mfma_f32_16x16x32_bf16 v[16:19], v[64:67], v[224:227], v[16:19]
	v_mfma_f32_16x16x32_bf16 v[104:107], v[68:71], v[92:95], v[96:99]
	v_mfma_f32_16x16x32_bf16 v[76:79], v[60:63], v[206:209], v[76:79]
	v_mfma_f32_16x16x32_bf16 v[72:75], v[68:71], v[206:209], v[72:75]
	v_mfma_f32_16x16x32_bf16 v[36:39], v[60:63], v[220:223], v[36:39]
	v_mfma_f32_16x16x32_bf16 v[32:35], v[68:71], v[220:223], v[32:35]
	v_mfma_f32_16x16x32_bf16 v[20:23], v[60:63], v[246:249], v[20:23]
	v_mfma_f32_16x16x32_bf16 v[16:19], v[68:71], v[246:249], v[16:19]
	s_setprio 0
	s_setprio 1
	v_mfma_f32_16x16x32_bf16 v[40:43], v[80:83], v[88:91], v[40:43]
	v_mfma_f32_16x16x32_bf16 v[100:103], v[84:87], v[92:95], v[40:43]
	v_mfma_f32_16x16x32_bf16 v[40:43], v[176:179], v[88:91], v[44:47]
	v_mfma_f32_16x16x32_bf16 v[96:99], v[180:183], v[92:95], v[40:43]
	v_mfma_f32_16x16x32_bf16 v[40:43], v[80:83], v[202:205], v[48:51]
	v_mfma_f32_16x16x32_bf16 v[60:63], v[84:87], v[206:209], v[40:43]
	v_mfma_f32_16x16x32_bf16 v[40:43], v[176:179], v[202:205], v[52:55]
	v_mfma_f32_16x16x32_bf16 v[28:31], v[80:83], v[210:213], v[28:31]
	v_mfma_f32_16x16x32_bf16 v[24:27], v[176:179], v[210:213], v[24:27]
	v_mfma_f32_16x16x32_bf16 v[10:13], v[80:83], v[224:227], v[12:15]
	v_mfma_f32_16x16x32_bf16 v[6:9], v[176:179], v[224:227], v[6:9]
	v_mfma_f32_16x16x32_bf16 v[56:59], v[180:183], v[206:209], v[40:43]
	v_mfma_f32_16x16x32_bf16 v[28:31], v[84:87], v[220:223], v[28:31]
	v_mfma_f32_16x16x32_bf16 v[24:27], v[180:183], v[220:223], v[24:27]
	v_mfma_f32_16x16x32_bf16 v[12:15], v[84:87], v[246:249], v[10:13]
	v_mfma_f32_16x16x32_bf16 v[8:11], v[180:183], v[246:249], v[6:9]
	s_barrier
	s_setprio 0
	s_add_i32 s39, s39, 2
	s_add_u32 s8, s8, 0x100
	s_addc_u32 s9, s9, 0
	s_add_u32 s33, s33, 0x100
	s_addc_u32 s38, s38, 0
	s_cmp_gt_u32 s39, 13
	s_cbranch_scc0 .LBB0_347
	s_and_b64 vcc, exec, s[20:21]
	s_cbranch_vccz .LBB0_350
	s_barrier

.LBB0_644:
	s_add_u32 s22, s20, 0xfffc0080
	s_addc_u32 s23, s21, -1
	s_add_i32 s45, 0, 0x10000
	s_cmp_eq_u32 s44, 12
	s_cselect_b32 s25, s11, s23
	s_cselect_b32 s24, s17, s22
	s_cselect_b32 s23, s9, s43
	s_cselect_b32 s22, s41, s42
	s_add_i32 s48, 0, 0x14000
	s_waitcnt vmcnt(0)
	v_add_u32_e32 v146, s45, v160
	v_add_u32_e32 v158, s48, v160
	ds_read_b128 v[134:137], v146
	ds_read_b128 v[138:141], v146 offset:1024
	ds_read_b128 v[142:145], v146 offset:2048
	ds_read_b128 v[146:149], v146 offset:3072
	ds_read_b128 v[164:167], v158
	ds_read_b128 v[168:171], v158 offset:1024
	ds_read_b128 v[172:175], v158 offset:2048
	ds_read_b128 v[176:179], v158 offset:3072
	v_lshl_add_u64 v[158:159], s[20:21], 0, v[154:155]
	s_add_i32 m0, s19, 0xc000
	ds_read_b128 v[180:183], v162
	ds_read_b128 v[184:187], v162 offset:1024
	ds_read_b128 v[188:191], v162 offset:2048
	ds_read_b128 v[192:195], v162 offset:3072
	ds_read_b128 v[196:199], v162 offset:4096
	ds_read_b128 v[200:203], v162 offset:5120
	ds_read_b128 v[204:207], v162 offset:6144
	ds_read_b128 v[208:211], v162 offset:7168
	global_load_lds_dwordx4 v[158:159], off
	v_lshl_add_u64 v[158:159], s[20:21], 0, v[156:157]
	s_add_i32 m0, s19, 0xe000
	s_nop 0
	global_load_lds_dwordx4 v[158:159], off
	s_waitcnt vmcnt(8)
	s_waitcnt lgkmcnt(0)
	s_setprio 1
	s_barrier
	v_mfma_f32_16x16x32_bf16 v[130:133], v[134:137], v[180:183], v[130:133]
	v_mfma_f32_16x16x32_bf16 v[126:129], v[142:145], v[180:183], v[126:129]
	v_mfma_f32_16x16x32_bf16 v[118:121], v[134:137], v[188:191], v[118:121]
	v_mfma_f32_16x16x32_bf16 v[110:113], v[142:145], v[188:191], v[110:113]
	v_mfma_f32_16x16x32_bf16 v[102:105], v[134:137], v[196:199], v[102:105]
	v_mfma_f32_16x16x32_bf16 v[94:97], v[142:145], v[196:199], v[94:97]
	v_mfma_f32_16x16x32_bf16 v[86:89], v[134:137], v[204:207], v[86:89]
	v_mfma_f32_16x16x32_bf16 v[78:81], v[142:145], v[204:207], v[78:81]
	v_mfma_f32_16x16x32_bf16 v[130:133], v[138:141], v[184:187], v[130:133]
	v_mfma_f32_16x16x32_bf16 v[126:129], v[146:149], v[184:187], v[126:129]
	v_mfma_f32_16x16x32_bf16 v[118:121], v[138:141], v[192:195], v[118:121]
	v_mfma_f32_16x16x32_bf16 v[110:113], v[146:149], v[192:195], v[110:113]
	v_mfma_f32_16x16x32_bf16 v[102:105], v[138:141], v[200:203], v[102:105]
	v_mfma_f32_16x16x32_bf16 v[94:97], v[146:149], v[200:203], v[94:97]
	v_mfma_f32_16x16x32_bf16 v[86:89], v[138:141], v[208:211], v[86:89]
	v_mfma_f32_16x16x32_bf16 v[78:81], v[146:149], v[208:211], v[78:81]
	s_setprio 0
	s_setprio 1
	v_mfma_f32_16x16x32_bf16 v[122:125], v[164:167], v[180:183], v[122:125]
	v_mfma_f32_16x16x32_bf16 v[114:117], v[172:175], v[180:183], v[114:117]
	v_mfma_f32_16x16x32_bf16 v[106:109], v[164:167], v[188:191], v[106:109]
	v_mfma_f32_16x16x32_bf16 v[98:101], v[172:175], v[188:191], v[98:101]
	v_mfma_f32_16x16x32_bf16 v[90:93], v[164:167], v[196:199], v[90:93]
	v_mfma_f32_16x16x32_bf16 v[82:85], v[172:175], v[196:199], v[82:85]
	v_mfma_f32_16x16x32_bf16 v[74:77], v[164:167], v[204:207], v[74:77]
	v_mfma_f32_16x16x32_bf16 v[70:73], v[172:175], v[204:207], v[70:73]
	v_mfma_f32_16x16x32_bf16 v[122:125], v[168:171], v[184:187], v[122:125]
	v_mfma_f32_16x16x32_bf16 v[114:117], v[176:179], v[184:187], v[114:117]
	v_mfma_f32_16x16x32_bf16 v[106:109], v[168:171], v[192:195], v[106:109]
	v_mfma_f32_16x16x32_bf16 v[98:101], v[176:179], v[192:195], v[98:101]
	v_mfma_f32_16x16x32_bf16 v[90:93], v[168:171], v[200:203], v[90:93]
	v_mfma_f32_16x16x32_bf16 v[82:85], v[176:179], v[200:203], v[82:85]
	v_mfma_f32_16x16x32_bf16 v[74:77], v[168:171], v[208:211], v[74:77]
	v_mfma_f32_16x16x32_bf16 v[70:73], v[176:179], v[208:211], v[70:73]
	s_barrier
	s_setprio 0
	s_add_i32 s45, s45, s30
	v_lshl_add_u64 v[158:159], s[22:23], 0, v[0:1]
	s_mov_b32 m0, s45
	ds_read_b128 v[180:183], v162 offset:16384
	ds_read_b128 v[184:187], v162 offset:17408
	ds_read_b128 v[188:191], v162 offset:18432
	ds_read_b128 v[192:195], v162 offset:19456
	ds_read_b128 v[196:199], v162 offset:20480
	ds_read_b128 v[200:203], v162 offset:21504
	ds_read_b128 v[204:207], v162 offset:22528
	ds_read_b128 v[208:211], v162 offset:23552
	global_load_lds_dwordx4 v[158:159], off
	s_add_i32 m0, s45, 0x2000
	s_add_u32 s60, s22, 0x40000
	v_lshl_add_u64 v[212:213], s[22:23], 0, v[152:153]
	s_addc_u32 s61, s23, 0
	s_add_i32 s45, s48, s30
	global_load_lds_dwordx4 v[212:213], off
	v_lshl_add_u64 v[214:215], s[60:61], 0, v[0:1]
	s_mov_b32 m0, s45
	v_lshl_add_u64 v[216:217], s[24:25], 0, v[150:151]
	global_load_lds_dwordx4 v[214:215], off
	v_lshl_add_u64 v[214:215], s[60:61], 0, v[152:153]
	s_add_i32 m0, s45, 0x2000
	s_nop 0
	global_load_lds_dwordx4 v[214:215], off
	v_lshl_add_u64 v[214:215], s[24:25], 0, v[2:3]
	s_mov_b32 m0, s19
	s_nop 0
	global_load_lds_dwordx4 v[214:215], off
	s_mov_b32 m0, s31
	s_nop 0
	global_load_lds_dwordx4 v[216:217], off
	s_waitcnt vmcnt(8)
	s_waitcnt lgkmcnt(0)
	s_setprio 1
	s_barrier
	v_mfma_f32_16x16x32_bf16 v[66:69], v[134:137], v[180:183], v[66:69]
	v_mfma_f32_16x16x32_bf16 v[62:65], v[142:145], v[180:183], v[62:65]
	v_mfma_f32_16x16x32_bf16 v[54:57], v[134:137], v[188:191], v[54:57]
	v_mfma_f32_16x16x32_bf16 v[46:49], v[142:145], v[188:191], v[46:49]
	v_mfma_f32_16x16x32_bf16 v[38:41], v[134:137], v[196:199], v[38:41]
	v_mfma_f32_16x16x32_bf16 v[30:33], v[142:145], v[196:199], v[30:33]
	v_mfma_f32_16x16x32_bf16 v[22:25], v[134:137], v[204:207], v[22:25]
	v_mfma_f32_16x16x32_bf16 v[14:17], v[142:145], v[204:207], v[14:17]
	v_mfma_f32_16x16x32_bf16 v[66:69], v[138:141], v[184:187], v[66:69]
	v_mfma_f32_16x16x32_bf16 v[62:65], v[146:149], v[184:187], v[62:65]
	v_mfma_f32_16x16x32_bf16 v[54:57], v[138:141], v[192:195], v[54:57]
	v_mfma_f32_16x16x32_bf16 v[46:49], v[146:149], v[192:195], v[46:49]
	v_mfma_f32_16x16x32_bf16 v[38:41], v[138:141], v[200:203], v[38:41]
	v_mfma_f32_16x16x32_bf16 v[30:33], v[146:149], v[200:203], v[30:33]
	v_mfma_f32_16x16x32_bf16 v[22:25], v[138:141], v[208:211], v[22:25]
	v_mfma_f32_16x16x32_bf16 v[14:17], v[146:149], v[208:211], v[14:17]
	s_setprio 0
	s_setprio 1
	v_mfma_f32_16x16x32_bf16 v[58:61], v[164:167], v[180:183], v[58:61]
	v_mfma_f32_16x16x32_bf16 v[50:53], v[172:175], v[180:183], v[50:53]
	v_mfma_f32_16x16x32_bf16 v[42:45], v[164:167], v[188:191], v[42:45]
	v_mfma_f32_16x16x32_bf16 v[34:37], v[172:175], v[188:191], v[34:37]
	v_mfma_f32_16x16x32_bf16 v[26:29], v[164:167], v[196:199], v[26:29]
	v_mfma_f32_16x16x32_bf16 v[18:21], v[172:175], v[196:199], v[18:21]
	v_mfma_f32_16x16x32_bf16 v[10:13], v[164:167], v[204:207], v[10:13]
	v_mfma_f32_16x16x32_bf16 v[6:9], v[172:175], v[204:207], v[6:9]
	v_mfma_f32_16x16x32_bf16 v[58:61], v[168:171], v[184:187], v[58:61]
	v_mfma_f32_16x16x32_bf16 v[50:53], v[176:179], v[184:187], v[50:53]
	v_mfma_f32_16x16x32_bf16 v[42:45], v[168:171], v[192:195], v[42:45]
	v_mfma_f32_16x16x32_bf16 v[34:37], v[176:179], v[192:195], v[34:37]
	v_mfma_f32_16x16x32_bf16 v[26:29], v[168:171], v[200:203], v[26:29]
	v_mfma_f32_16x16x32_bf16 v[18:21], v[176:179], v[200:203], v[18:21]
	v_mfma_f32_16x16x32_bf16 v[10:13], v[168:171], v[208:211], v[10:13]
	v_mfma_f32_16x16x32_bf16 v[6:9], v[176:179], v[208:211], v[6:9]
	s_barrier
	s_setprio 0
	s_add_i32 s45, 0, 0x18000
	s_add_i32 s48, 0, 0x1c000
	v_add_u32_e32 v146, s45, v160
	v_add_u32_e32 v163, s48, v160
	ds_read_b128 v[134:137], v146
	ds_read_b128 v[138:141], v146 offset:1024
	ds_read_b128 v[142:145], v146 offset:2048
	ds_read_b128 v[146:149], v146 offset:3072
	ds_read_b128 v[164:167], v163
	ds_read_b128 v[168:171], v163 offset:1024
	ds_read_b128 v[172:175], v163 offset:2048
	ds_read_b128 v[176:179], v163 offset:3072
	s_add_u32 s24, s24, 0x40000
	s_addc_u32 s25, s25, 0
	s_mov_b32 m0, s33
	v_lshl_add_u64 v[220:221], s[24:25], 0, v[2:3]
	ds_read_b128 v[180:183], v162 offset:32768
	ds_read_b128 v[184:187], v162 offset:33792
	ds_read_b128 v[188:191], v162 offset:34816
	ds_read_b128 v[192:195], v162 offset:35840
	ds_read_b128 v[196:199], v162 offset:36864
	ds_read_b128 v[200:203], v162 offset:37888
	ds_read_b128 v[204:207], v162 offset:38912
	ds_read_b128 v[208:211], v162 offset:39936
	global_load_lds_dwordx4 v[220:221], off
	v_lshl_add_u64 v[220:221], s[24:25], 0, v[150:151]
	s_mov_b32 m0, s34
	s_nop 0
	global_load_lds_dwordx4 v[220:221], off
	s_waitcnt vmcnt(8)
	s_waitcnt lgkmcnt(0)
	s_setprio 1
	s_barrier
	v_mfma_f32_16x16x32_bf16 v[130:133], v[134:137], v[180:183], v[130:133]
	v_mfma_f32_16x16x32_bf16 v[126:129], v[142:145], v[180:183], v[126:129]
	v_mfma_f32_16x16x32_bf16 v[118:121], v[134:137], v[188:191], v[118:121]
	v_mfma_f32_16x16x32_bf16 v[110:113], v[142:145], v[188:191], v[110:113]
	v_mfma_f32_16x16x32_bf16 v[102:105], v[134:137], v[196:199], v[102:105]
	v_mfma_f32_16x16x32_bf16 v[94:97], v[142:145], v[196:199], v[94:97]
	v_mfma_f32_16x16x32_bf16 v[86:89], v[134:137], v[204:207], v[86:89]
	v_mfma_f32_16x16x32_bf16 v[78:81], v[142:145], v[204:207], v[78:81]
	v_mfma_f32_16x16x32_bf16 v[130:133], v[138:141], v[184:187], v[130:133]
	v_mfma_f32_16x16x32_bf16 v[126:129], v[146:149], v[184:187], v[126:129]
	v_mfma_f32_16x16x32_bf16 v[118:121], v[138:141], v[192:195], v[118:121]
	v_mfma_f32_16x16x32_bf16 v[110:113], v[146:149], v[192:195], v[110:113]
	v_mfma_f32_16x16x32_bf16 v[102:105], v[138:141], v[200:203], v[102:105]
	v_mfma_f32_16x16x32_bf16 v[94:97], v[146:149], v[200:203], v[94:97]
	v_mfma_f32_16x16x32_bf16 v[86:89], v[138:141], v[208:211], v[86:89]
	v_mfma_f32_16x16x32_bf16 v[78:81], v[146:149], v[208:211], v[78:81]
	s_setprio 0
	s_setprio 1
	v_mfma_f32_16x16x32_bf16 v[122:125], v[164:167], v[180:183], v[122:125]
	v_mfma_f32_16x16x32_bf16 v[114:117], v[172:175], v[180:183], v[114:117]
	v_mfma_f32_16x16x32_bf16 v[106:109], v[164:167], v[188:191], v[106:109]
	v_mfma_f32_16x16x32_bf16 v[98:101], v[172:175], v[188:191], v[98:101]
	v_mfma_f32_16x16x32_bf16 v[90:93], v[164:167], v[196:199], v[90:93]
	v_mfma_f32_16x16x32_bf16 v[82:85], v[172:175], v[196:199], v[82:85]
	v_mfma_f32_16x16x32_bf16 v[74:77], v[164:167], v[204:207], v[74:77]
	v_mfma_f32_16x16x32_bf16 v[70:73], v[172:175], v[204:207], v[70:73]
	v_mfma_f32_16x16x32_bf16 v[122:125], v[168:171], v[184:187], v[122:125]
	v_mfma_f32_16x16x32_bf16 v[114:117], v[176:179], v[184:187], v[114:117]
	v_mfma_f32_16x16x32_bf16 v[106:109], v[168:171], v[192:195], v[106:109]
	v_mfma_f32_16x16x32_bf16 v[98:101], v[176:179], v[192:195], v[98:101]
	v_mfma_f32_16x16x32_bf16 v[90:93], v[168:171], v[200:203], v[90:93]
	v_mfma_f32_16x16x32_bf16 v[82:85], v[176:179], v[200:203], v[82:85]
	v_mfma_f32_16x16x32_bf16 v[74:77], v[168:171], v[208:211], v[74:77]
	v_mfma_f32_16x16x32_bf16 v[70:73], v[176:179], v[208:211], v[70:73]
	s_barrier
	s_setprio 0
	s_add_i32 s24, s45, s30
	v_lshl_add_u64 v[158:159], v[158:159], 0, s[50:51]
	s_mov_b32 m0, s24
	ds_read_b128 v[180:183], v162 offset:49152
	ds_read_b128 v[184:187], v162 offset:50176
	ds_read_b128 v[188:191], v162 offset:51200
	ds_read_b128 v[192:195], v162 offset:52224
	ds_read_b128 v[196:199], v162 offset:53248
	ds_read_b128 v[200:203], v162 offset:54272
	ds_read_b128 v[204:207], v162 offset:55296
	ds_read_b128 v[208:211], v162 offset:56320
	global_load_lds_dwordx4 v[158:159], off
	s_add_i32 m0, s24, 0x2000
	s_add_u32 s22, s22, 0x40080
	v_lshl_add_u64 v[158:159], v[212:213], 0, s[50:51]
	s_addc_u32 s23, s23, 0
	s_add_i32 s24, s48, s30
	global_load_lds_dwordx4 v[158:159], off
	v_lshl_add_u64 v[158:159], s[22:23], 0, v[0:1]
	s_mov_b32 m0, s24
	s_nop 0
	global_load_lds_dwordx4 v[158:159], off
	v_lshl_add_u64 v[158:159], s[22:23], 0, v[152:153]
	s_add_i32 m0, s24, 0x2000
	s_nop 0
	global_load_lds_dwordx4 v[158:159], off
	v_lshl_add_u64 v[158:159], v[214:215], 0, s[50:51]
	s_mov_b32 m0, s35
	s_nop 0
	global_load_lds_dwordx4 v[158:159], off
	v_lshl_add_u64 v[158:159], v[216:217], 0, s[50:51]
	s_mov_b32 m0, s36
	s_nop 0
	global_load_lds_dwordx4 v[158:159], off
	s_waitcnt vmcnt(8)
	s_waitcnt lgkmcnt(0)
	s_setprio 1
	s_barrier
	v_mfma_f32_16x16x32_bf16 v[66:69], v[134:137], v[180:183], v[66:69]
	v_mfma_f32_16x16x32_bf16 v[62:65], v[142:145], v[180:183], v[62:65]
	v_mfma_f32_16x16x32_bf16 v[54:57], v[134:137], v[188:191], v[54:57]
	v_mfma_f32_16x16x32_bf16 v[46:49], v[142:145], v[188:191], v[46:49]
	v_mfma_f32_16x16x32_bf16 v[38:41], v[134:137], v[196:199], v[38:41]
	v_mfma_f32_16x16x32_bf16 v[30:33], v[142:145], v[196:199], v[30:33]
	v_mfma_f32_16x16x32_bf16 v[22:25], v[134:137], v[204:207], v[22:25]
	v_mfma_f32_16x16x32_bf16 v[14:17], v[142:145], v[204:207], v[14:17]
	v_mfma_f32_16x16x32_bf16 v[66:69], v[138:141], v[184:187], v[66:69]
	v_mfma_f32_16x16x32_bf16 v[62:65], v[146:149], v[184:187], v[62:65]
	v_mfma_f32_16x16x32_bf16 v[54:57], v[138:141], v[192:195], v[54:57]
	v_mfma_f32_16x16x32_bf16 v[46:49], v[146:149], v[192:195], v[46:49]
	v_mfma_f32_16x16x32_bf16 v[38:41], v[138:141], v[200:203], v[38:41]
	v_mfma_f32_16x16x32_bf16 v[30:33], v[146:149], v[200:203], v[30:33]
	v_mfma_f32_16x16x32_bf16 v[22:25], v[138:141], v[208:211], v[22:25]
	v_mfma_f32_16x16x32_bf16 v[14:17], v[146:149], v[208:211], v[14:17]
	s_setprio 0
	s_setprio 1
	v_mfma_f32_16x16x32_bf16 v[58:61], v[164:167], v[180:183], v[58:61]
	v_mfma_f32_16x16x32_bf16 v[50:53], v[172:175], v[180:183], v[50:53]
	v_mfma_f32_16x16x32_bf16 v[42:45], v[164:167], v[188:191], v[42:45]
	v_mfma_f32_16x16x32_bf16 v[34:37], v[172:175], v[188:191], v[34:37]
	v_mfma_f32_16x16x32_bf16 v[26:29], v[164:167], v[196:199], v[26:29]
	v_mfma_f32_16x16x32_bf16 v[18:21], v[172:175], v[196:199], v[18:21]
	v_mfma_f32_16x16x32_bf16 v[10:13], v[164:167], v[204:207], v[10:13]
	v_mfma_f32_16x16x32_bf16 v[6:9], v[172:175], v[204:207], v[6:9]
	v_mfma_f32_16x16x32_bf16 v[58:61], v[168:171], v[184:187], v[58:61]
	v_mfma_f32_16x16x32_bf16 v[50:53], v[176:179], v[184:187], v[50:53]
	v_mfma_f32_16x16x32_bf16 v[42:45], v[168:171], v[192:195], v[42:45]
	v_mfma_f32_16x16x32_bf16 v[34:37], v[176:179], v[192:195], v[34:37]
	v_mfma_f32_16x16x32_bf16 v[26:29], v[168:171], v[200:203], v[26:29]
	v_mfma_f32_16x16x32_bf16 v[18:21], v[176:179], v[200:203], v[18:21]
	v_mfma_f32_16x16x32_bf16 v[10:13], v[168:171], v[208:211], v[10:13]
	v_mfma_f32_16x16x32_bf16 v[6:9], v[176:179], v[208:211], v[6:9]
	s_barrier
	s_setprio 0
	s_add_i32 s44, s44, 2
	s_add_u32 s20, s20, 0x100
	s_addc_u32 s21, s21, 0
	s_add_u32 s42, s42, 0x100
	s_addc_u32 s43, s43, 0
	s_cmp_gt_u32 s44, 13
	s_cbranch_scc0 .LBB0_644
	s_and_b64 vcc, exec, s[6:7]
	s_cbranch_vccz .LBB0_647
	s_barrier
